# adds: GEMM K-loops without per-block s_setprio flips, one static s_setprio 1 for waves 0-3 per GEMM phase
# speedup vs baseline: 1.0032x; 1.0015x over previous
; #define PG8_STAGE(bufoff, gbase, voff) do { _Pragma("unroll") for (int _i = 0; _i < 2; ++_i) \
;         __builtin_amdgcn_global_load_lds((const unsigned*)((const char*)(gbase) + (voff)[_i]), (PG8_LAS unsigned*)(lds + (bufoff) + ldsw + _i * 8192), 16, 0, 0); } while (0)
; #define PG8_WAIT_V(n) asm volatile("s_waitcnt vmcnt(" #n ")" ::: "memory")
; #define PG8_BAR __builtin_amdgcn_s_barrier()
; template <class Epi, class Sched, bool ALIGN_EPI = false, bool SP2 = false>
; __device__ __forceinline__ void gemm_phase(PG8_LAS unsigned char* lds, const Gemm g, const Sched& S, const Epi& E) {
;     ...
;     for (int i = 0; i < 2; ++i) { int R, C; stage_rc(tid * 16 + i * 8192, R, C); const int Rb = Epi::PERM ? ((R & ~31) + perm32(R & 31)) : R;
;         voffA[i] = (unsigned)(R * K + C) * 2u; voffB[i] = (unsigned)(Rb * K + C) * 2u; }
;     const size_t kstep = (size_t)(BK * 2);
;     const size_t hstep = (size_t)HALF * K * 2;
;     const size_t tstep = 2 * hstep;
;     const unsigned ldsw = (unsigned)wid * 1024u;
;     const int aoff = lds_byte(wr * 64 + fr, fq * 8), boff = lds_byte(wc * 32 + fr, fq * 8);
;     ...
;         PG8_STAGE(PG8_SB(0, 0), cB, voffB); PG8_STAGE(PG8_SB(0, 1), cB + hstep, voffB); PG8_STAGE(PG8_SA(0, 0), cA, voffA); PG8_STAGE(PG8_SA(0, 1), cA + hstep, voffA);
;         if (wr == 1) PG8_BAR;
;         PG8_WAIT_V(2); PG8_BAR;
;         PG8_STAGE(PG8_SB(1, 0), cB + kstep, voffB); PG8_STAGE(PG8_SA(1, 0), cA + kstep, voffA); PG8_STAGE(PG8_SB(1, 1), cB + hstep + kstep, voffB);
;         PG8_WAIT_V(6); PG8_BAR;
.LBB0_55:
	s_lshl_b32 s8, s8, 5
	s_and_b32 s14, s8, 0x60
	s_mov_b64 s[8:9], 0x80
	s_add_i32 m0, s47, 0x18000
	v_lshl_add_u64 v[6:7], v[6:7], 0, s[8:9]
	s_lshl_b32 s11, s10, 13
	s_lshl_b32 s15, s14, 7
	s_waitcnt vmcnt(2)
	s_barrier
	global_load_lds_dwordx4 v[6:7], off
	v_lshl_add_u64 v[4:5], v[4:5], 0, s[8:9]
	s_add_i32 m0, s47, 0x1a000
	s_add_i32 s77, s47, 0x8000
	s_add_i32 s78, s47, 0xa000
	global_load_lds_dwordx4 v[4:5], off
	v_lshl_add_u64 v[0:1], v[0:1], 0, s[8:9]
	s_mov_b32 m0, s77
	s_add_u32 s12, s68, 0x80080
	global_load_lds_dwordx4 v[0:1], off
	v_lshl_add_u64 v[0:1], v[2:3], 0, s[8:9]
	s_mov_b32 m0, s78
	s_addc_u32 s13, s69, 0
	global_load_lds_dwordx4 v[0:1], off
	s_add_i32 m0, s47, 0x1c000
	v_lshl_add_u64 v[0:1], s[12:13], 0, v[132:133]
	global_load_lds_dwordx4 v[0:1], off
	v_lshl_add_u64 v[0:1], s[12:13], 0, v[128:129]
	s_add_i32 m0, s47, 0x1e000
	s_sext_i32_i16 s86, s0
	global_load_lds_dwordx4 v[0:1], off
	v_and_b32_e32 v0, 15, v220
	v_lshlrev_b32_e32 v1, 1, v11
	v_lshlrev_b32_e32 v2, 2, v220
	v_lshlrev_b32_e32 v3, 6, v220
	s_movk_i32 s0, 0x3c0
	v_lshl_or_b32 v148, s10, 6, v0
	v_lshl_or_b32 v0, v0, 6, v1
	v_and_b32_e32 v2, 32, v2
	v_and_or_b32 v1, v3, s0, v1
	v_bitop3_b32 v149, s15, v1, v2 bitop3:0xf6
	v_lshlrev_b32_e32 v1, 9, v220
	v_bitop3_b32 v0, v0, s11, v2 bitop3:0xde
	v_and_b32_e32 v1, 0x70000, v1
	v_lshlrev_b32_e32 v2, 12, v12
	v_or3_b32 v1, v9, v1, v2
	v_add_u32_e32 v138, v1, v10
	v_lshlrev_b32_e32 v1, 5, v8
	s_waitcnt vmcnt(6)
	s_cmpk_lt_u32 s1, 0x100
	v_and_b32_e32 v1, 0xf0000, v1
	s_cselect_b64 s[10:11], -1, 0
	v_or3_b32 v1, v9, v1, v2
	s_add_i32 s80, 0, 0x10000
	s_add_i32 s81, 0, 0x14000
	s_waitcnt lgkmcnt(0)
	s_ashr_i32 s79, s33, 31
	v_or_b32_e32 v150, s14, v11
	v_lshlrev_b32_e32 v230, 11, v148
	v_lshl_add_u32 v230, v150, 1, v230
	v_mov_b32_e32 v139, v137
	v_add_u32_e32 v140, v1, v10
	v_mov_b32_e32 v141, v137
	v_mov_b64_e32 v[142:143], 0x1600
	v_mov_b64_e32 v[144:145], 0x15ff
	v_add_u32_e32 v151, s80, v149
	v_add_u32_e32 v152, s81, v149
	v_add_u32_e32 v153, 0, v0
	s_mov_b64 s[12:13], 0x40000
	s_mov_b32 s82, 0x40000
	s_mov_b64 s[14:15], 0x48000
	s_mov_b32 s83, 0x48000
	s_mov_b64 s[16:17], 0x50000
	s_mov_b32 s84, 0x50000
	s_mov_b64 s[18:19], 0x58000
	s_mov_b32 s85, 0x58000
	s_barrier
	s_waitcnt vmcnt(0)
	v_readfirstlane_b32 s101, v220
	s_nop 3
	s_lshr_b32 s101, s101, 6
	s_cmp_lt_u32 s101, 4
	s_cbranch_scc0 .Lprio_skip_0
	s_setprio 1
.Lprio_skip_0:
	s_branch .LBB0_58

; #define PG8_STAGE(bufoff, gbase, voff) do { _Pragma("unroll") for (int _i = 0; _i < 2; ++_i) \
;         __builtin_amdgcn_global_load_lds((const unsigned*)((const char*)(gbase) + (voff)[_i]), (PG8_LAS unsigned*)(lds + (bufoff) + ldsw + _i * 8192), 16, 0, 0); } while (0)
; #define PG8_LDA(dst, b, h) do { _Pragma("unroll") for (int m = 0; m < 4; ++m) _Pragma("unroll") for (int k = 0; k < 2; ++k) dst[m][k] = *(const PG8_LAS bf16x8*)(lds + PG8_SA(b, h) + aoff + m * 2048 + k * 1024); } while (0)
; #define PG8_LDB(dst, b, h) do { _Pragma("unroll") for (int n = 0; n < 2; ++n) _Pragma("unroll") for (int k = 0; k < 2; ++k) dst[n][k] = *(const PG8_LAS bf16x8*)(lds + PG8_SB(b, h) + boff + n * 2048 + k * 1024); } while (0)
; #define PG8_MMA(ai, bj, At, Bt) do { __builtin_amdgcn_s_setprio(1); _Pragma("unroll") for (int m = 0; m < 4; ++m) _Pragma("unroll") for (int n = 0; n < 2; ++n) _Pragma("unroll") for (int k = 0; k < 2; ++k) \
;         acc[ai][bj][m][n] = __builtin_amdgcn_mfma_f32_16x16x32_bf16(Bt[n][k], At[m][k], acc[ai][bj][m][n], 0, 0, 0); __builtin_amdgcn_s_setprio(0); } while (0)
; #define PG8_WAIT_V(n) asm volatile("s_waitcnt vmcnt(" #n ")" ::: "memory")
; #define PG8_WAIT_L(n) asm volatile("s_waitcnt lgkmcnt(" #n ")" ::: "memory")
; #define PG8_BAR __builtin_amdgcn_s_barrier()
; #define PG8_SCHED __builtin_amdgcn_sched_barrier(0)
; template <class Epi, class Sched, bool ALIGN_EPI = false, bool SP2 = false>
; __device__ __forceinline__ void gemm_phase(PG8_LAS unsigned char* lds, const Gemm g, const Sched& S, const Epi& E) {
;     ...
;             PG8_LDB(B0, 0, 0); PG8_LDB(B1, 0, 1); PG8_SCHED; PG8_LDA(At, 0, 0); PG8_STAGE(PG8_SA(1, 1), a1 + hstep, voffA);
;             PG8_WAIT_V(8); PG8_WAIT_L(0); PG8_BAR; PG8_MMA(0, 0, At, B0); PG8_MMA(0, 1, At, B1); PG8_BAR; PG8_SCHED;
;             PG8_LDA(At, 0, 1); PG8_STAGE(PG8_SB(0, 0), b2, voffB); PG8_STAGE(PG8_SB(0, 1), b2 + hstep, voffB); PG8_STAGE(PG8_SA(0, 0), a2, voffA);
;             PG8_WAIT_V(8); PG8_WAIT_L(0); PG8_BAR; PG8_MMA(1, 0, At, B0); PG8_MMA(1, 1, At, B1); PG8_BAR; PG8_SCHED;
.LBB0_61:
	ds_read_b128 v[154:157], v151
	ds_read_b128 v[158:161], v151 offset:1024
	ds_read_b128 v[162:165], v151 offset:2048
	ds_read_b128 v[166:169], v151 offset:3072
	ds_read_b128 v[170:173], v152
	ds_read_b128 v[174:177], v152 offset:1024
	ds_read_b128 v[178:181], v152 offset:2048
	ds_read_b128 v[182:185], v152 offset:3072
	s_add_u32 s52, s54, 0xfff80080
	s_addc_u32 s53, s55, -1
	s_cmp_eq_u32 s91, 28
	s_cselect_b32 s71, s23, s53
	s_cselect_b32 s70, s87, s52
	s_cselect_b32 s69, s21, s90
	s_cselect_b32 s68, s88, s89
	s_add_i32 m0, s47, 0xc000
	ds_read_b128 v[186:189], v153
	ds_read_b128 v[190:193], v153 offset:1024
	ds_read_b128 v[194:197], v153 offset:2048
	ds_read_b128 v[198:201], v153 offset:3072
	ds_read_b128 v[202:205], v153 offset:4096
	ds_read_b128 v[206:209], v153 offset:5120
	ds_read_b128 v[210:213], v153 offset:6144
	ds_read_b128 v[214:217], v153 offset:7168
	global_load_lds_dwordx4 v138, s[54:55]
	s_add_i32 m0, s47, 0xe000
	s_nop 0
	global_load_lds_dwordx4 v140, s[54:55]
	s_waitcnt vmcnt(8)
	s_waitcnt lgkmcnt(0)
	s_barrier
	s_waitcnt lgkmcnt(0)
	v_mfma_f32_16x16x32_bf16 v[124:127], v[154:157], v[186:189], v[124:127]
	v_mfma_f32_16x16x32_bf16 v[120:123], v[162:165], v[186:189], v[120:123]
	v_mfma_f32_16x16x32_bf16 v[116:119], v[154:157], v[194:197], v[116:119]
	v_mfma_f32_16x16x32_bf16 v[108:111], v[162:165], v[194:197], v[108:111]
	v_mfma_f32_16x16x32_bf16 v[100:103], v[154:157], v[202:205], v[100:103]
	v_mfma_f32_16x16x32_bf16 v[92:95], v[162:165], v[202:205], v[92:95]
	v_mfma_f32_16x16x32_bf16 v[84:87], v[154:157], v[210:213], v[84:87]
	v_mfma_f32_16x16x32_bf16 v[76:79], v[162:165], v[210:213], v[76:79]
	v_mfma_f32_16x16x32_bf16 v[124:127], v[158:161], v[190:193], v[124:127]
	v_mfma_f32_16x16x32_bf16 v[120:123], v[166:169], v[190:193], v[120:123]
	v_mfma_f32_16x16x32_bf16 v[116:119], v[158:161], v[198:201], v[116:119]
	v_mfma_f32_16x16x32_bf16 v[108:111], v[166:169], v[198:201], v[108:111]
	v_mfma_f32_16x16x32_bf16 v[100:103], v[158:161], v[206:209], v[100:103]
	v_mfma_f32_16x16x32_bf16 v[92:95], v[166:169], v[206:209], v[92:95]
	v_mfma_f32_16x16x32_bf16 v[84:87], v[158:161], v[214:217], v[84:87]
	v_mfma_f32_16x16x32_bf16 v[76:79], v[166:169], v[214:217], v[76:79]
	v_mfma_f32_16x16x32_bf16 v[112:115], v[170:173], v[186:189], v[112:115]
	v_mfma_f32_16x16x32_bf16 v[104:107], v[178:181], v[186:189], v[104:107]
	v_mfma_f32_16x16x32_bf16 v[96:99], v[170:173], v[194:197], v[96:99]
	v_mfma_f32_16x16x32_bf16 v[88:91], v[178:181], v[194:197], v[88:91]
	v_mfma_f32_16x16x32_bf16 v[80:83], v[170:173], v[202:205], v[80:83]
	v_mfma_f32_16x16x32_bf16 v[72:75], v[178:181], v[202:205], v[72:75]
	v_mfma_f32_16x16x32_bf16 v[68:71], v[170:173], v[210:213], v[68:71]
	v_mfma_f32_16x16x32_bf16 v[64:67], v[178:181], v[210:213], v[64:67]
	v_mfma_f32_16x16x32_bf16 v[112:115], v[174:177], v[190:193], v[112:115]
	v_mfma_f32_16x16x32_bf16 v[104:107], v[182:185], v[190:193], v[104:107]
	v_mfma_f32_16x16x32_bf16 v[96:99], v[174:177], v[198:201], v[96:99]
	v_mfma_f32_16x16x32_bf16 v[88:91], v[182:185], v[198:201], v[88:91]
	v_mfma_f32_16x16x32_bf16 v[80:83], v[174:177], v[206:209], v[80:83]
	v_mfma_f32_16x16x32_bf16 v[72:75], v[182:185], v[206:209], v[72:75]
	v_mfma_f32_16x16x32_bf16 v[68:71], v[174:177], v[214:217], v[68:71]
	v_mfma_f32_16x16x32_bf16 v[64:67], v[182:185], v[214:217], v[64:67]
	s_barrier
	s_add_i32 s52, s80, s3
	s_mov_b32 m0, s52
	ds_read_b128 v[186:189], v153 offset:16384
	ds_read_b128 v[190:193], v153 offset:17408
	ds_read_b128 v[194:197], v153 offset:18432
	ds_read_b128 v[198:201], v153 offset:19456
	ds_read_b128 v[202:205], v153 offset:20480
	ds_read_b128 v[206:209], v153 offset:21504
	ds_read_b128 v[210:213], v153 offset:22528
	ds_read_b128 v[214:217], v153 offset:23552
	global_load_lds_dwordx4 v132, s[68:69]
	s_add_i32 m0, s52, 0x2000
	s_add_u32 s92, s68, 0x80000
	s_addc_u32 s93, s69, 0
	s_add_i32 s52, s81, s3
	global_load_lds_dwordx4 v128, s[68:69]
	s_mov_b32 m0, s52
	s_nop 0
	global_load_lds_dwordx4 v132, s[92:93]
	s_add_i32 m0, s52, 0x2000
	s_nop 0
	global_load_lds_dwordx4 v128, s[92:93]
	s_mov_b32 m0, s47
	s_nop 0
	global_load_lds_dwordx4 v134, s[70:71]
	s_mov_b32 m0, s73
	s_nop 0
	global_load_lds_dwordx4 v130, s[70:71]
	s_waitcnt vmcnt(8)
	s_waitcnt lgkmcnt(0)
	s_barrier
	s_waitcnt lgkmcnt(0)
	v_mfma_f32_16x16x32_bf16 v[60:63], v[154:157], v[186:189], v[60:63]
	v_mfma_f32_16x16x32_bf16 v[56:59], v[162:165], v[186:189], v[56:59]
	v_mfma_f32_16x16x32_bf16 v[52:55], v[154:157], v[194:197], v[52:55]
	v_mfma_f32_16x16x32_bf16 v[44:47], v[162:165], v[194:197], v[44:47]
	v_mfma_f32_16x16x32_bf16 v[36:39], v[154:157], v[202:205], v[36:39]
	v_mfma_f32_16x16x32_bf16 v[28:31], v[162:165], v[202:205], v[28:31]
	v_mfma_f32_16x16x32_bf16 v[20:23], v[154:157], v[210:213], v[20:23]
	v_mfma_f32_16x16x32_bf16 v[12:15], v[162:165], v[210:213], v[12:15]
	v_mfma_f32_16x16x32_bf16 v[60:63], v[158:161], v[190:193], v[60:63]
	v_mfma_f32_16x16x32_bf16 v[56:59], v[166:169], v[190:193], v[56:59]
	v_mfma_f32_16x16x32_bf16 v[52:55], v[158:161], v[198:201], v[52:55]
	v_mfma_f32_16x16x32_bf16 v[44:47], v[166:169], v[198:201], v[44:47]
	v_mfma_f32_16x16x32_bf16 v[36:39], v[158:161], v[206:209], v[36:39]
	v_mfma_f32_16x16x32_bf16 v[28:31], v[166:169], v[206:209], v[28:31]
	v_mfma_f32_16x16x32_bf16 v[20:23], v[158:161], v[214:217], v[20:23]
	v_mfma_f32_16x16x32_bf16 v[12:15], v[166:169], v[214:217], v[12:15]
	v_mfma_f32_16x16x32_bf16 v[48:51], v[170:173], v[186:189], v[48:51]
	v_mfma_f32_16x16x32_bf16 v[40:43], v[178:181], v[186:189], v[40:43]
	v_mfma_f32_16x16x32_bf16 v[32:35], v[170:173], v[194:197], v[32:35]
	v_mfma_f32_16x16x32_bf16 v[24:27], v[178:181], v[194:197], v[24:27]
	v_mfma_f32_16x16x32_bf16 v[16:19], v[170:173], v[202:205], v[16:19]
	v_mfma_f32_16x16x32_bf16 v[8:11], v[178:181], v[202:205], v[8:11]
	v_mfma_f32_16x16x32_bf16 v[4:7], v[170:173], v[210:213], v[4:7]
	v_mfma_f32_16x16x32_bf16 v[0:3], v[178:181], v[210:213], v[0:3]
	v_mfma_f32_16x16x32_bf16 v[48:51], v[174:177], v[190:193], v[48:51]
	v_mfma_f32_16x16x32_bf16 v[40:43], v[182:185], v[190:193], v[40:43]
	v_mfma_f32_16x16x32_bf16 v[32:35], v[174:177], v[198:201], v[32:35]
	v_mfma_f32_16x16x32_bf16 v[24:27], v[182:185], v[198:201], v[24:27]
	v_mfma_f32_16x16x32_bf16 v[16:19], v[174:177], v[206:209], v[16:19]
	v_mfma_f32_16x16x32_bf16 v[8:11], v[182:185], v[206:209], v[8:11]
	v_mfma_f32_16x16x32_bf16 v[4:7], v[174:177], v[214:217], v[4:7]
	v_mfma_f32_16x16x32_bf16 v[0:3], v[182:185], v[214:217], v[0:3]
	s_barrier
; #define PG8_STAGE(bufoff, gbase, voff) do { _Pragma("unroll") for (int _i = 0; _i < 2; ++_i) \
;         __builtin_amdgcn_global_load_lds((const unsigned*)((const char*)(gbase) + (voff)[_i]), (PG8_LAS unsigned*)(lds + (bufoff) + ldsw + _i * 8192), 16, 0, 0); } while (0)
; #define PG8_LDA(dst, b, h) do { _Pragma("unroll") for (int m = 0; m < 4; ++m) _Pragma("unroll") for (int k = 0; k < 2; ++k) dst[m][k] = *(const PG8_LAS bf16x8*)(lds + PG8_SA(b, h) + aoff + m * 2048 + k * 1024); } while (0)
; #define PG8_LDB(dst, b, h) do { _Pragma("unroll") for (int n = 0; n < 2; ++n) _Pragma("unroll") for (int k = 0; k < 2; ++k) dst[n][k] = *(const PG8_LAS bf16x8*)(lds + PG8_SB(b, h) + boff + n * 2048 + k * 1024); } while (0)
; #define PG8_MMA(ai, bj, At, Bt) do { __builtin_amdgcn_s_setprio(1); _Pragma("unroll") for (int m = 0; m < 4; ++m) _Pragma("unroll") for (int n = 0; n < 2; ++n) _Pragma("unroll") for (int k = 0; k < 2; ++k) \
;         acc[ai][bj][m][n] = __builtin_amdgcn_mfma_f32_16x16x32_bf16(Bt[n][k], At[m][k], acc[ai][bj][m][n], 0, 0, 0); __builtin_amdgcn_s_setprio(0); } while (0)
; #define PG8_WAIT_V(n) asm volatile("s_waitcnt vmcnt(" #n ")" ::: "memory")
; #define PG8_WAIT_L(n) asm volatile("s_waitcnt lgkmcnt(" #n ")" ::: "memory")
; #define PG8_BAR __builtin_amdgcn_s_barrier()
; #define PG8_SCHED __builtin_amdgcn_sched_barrier(0)
; template <class Epi, class Sched, bool ALIGN_EPI = false, bool SP2 = false>
; __device__ __forceinline__ void gemm_phase(PG8_LAS unsigned char* lds, const Gemm g, const Sched& S, const Epi& E) {
;     ...
;             PG8_LDB(B0, 1, 0); PG8_LDB(B1, 1, 1); PG8_SCHED; PG8_LDA(At, 1, 0); PG8_STAGE(PG8_SA(0, 1), a2 + hstep, voffA);
;             PG8_WAIT_V(8); PG8_WAIT_L(0); PG8_BAR; PG8_MMA(0, 0, At, B0); PG8_MMA(0, 1, At, B1); PG8_BAR; PG8_SCHED;
;             PG8_LDA(At, 1, 1); PG8_STAGE(PG8_SB(1, 0), b3, voffB); PG8_STAGE(PG8_SB(1, 1), b3 + hstep, voffB); PG8_STAGE(PG8_SA(1, 0), a3, voffA);
;             PG8_WAIT_V(8); PG8_WAIT_L(0); PG8_BAR; PG8_MMA(1, 0, At, B0); PG8_MMA(1, 1, At, B1); PG8_BAR; PG8_SCHED;
	s_add_i32 s52, 0, 0x18000
	v_add_u32_e32 v136, s52, v149
	s_add_i32 s53, 0, 0x1c000
	ds_read_b128 v[154:157], v136
	ds_read_b128 v[158:161], v136 offset:1024
	ds_read_b128 v[162:165], v136 offset:2048
	ds_read_b128 v[166:169], v136 offset:3072
	v_add_u32_e32 v136, s53, v149
	ds_read_b128 v[170:173], v136
	ds_read_b128 v[174:177], v136 offset:1024
	ds_read_b128 v[178:181], v136 offset:2048
	ds_read_b128 v[182:185], v136 offset:3072
	s_add_u32 s70, s70, 0x80000
	s_addc_u32 s71, s71, 0
	s_mov_b32 m0, s74
	ds_read_b128 v[186:189], v153 offset:32768
	ds_read_b128 v[190:193], v153 offset:33792
	ds_read_b128 v[194:197], v153 offset:34816
	ds_read_b128 v[198:201], v153 offset:35840
	ds_read_b128 v[202:205], v153 offset:36864
	ds_read_b128 v[206:209], v153 offset:37888
	ds_read_b128 v[210:213], v153 offset:38912
	ds_read_b128 v[214:217], v153 offset:39936
	global_load_lds_dwordx4 v134, s[70:71]
	s_mov_b32 m0, s75
	s_nop 0
	global_load_lds_dwordx4 v130, s[70:71]
	s_waitcnt vmcnt(8)
	s_waitcnt lgkmcnt(0)
	s_barrier
	s_waitcnt lgkmcnt(0)
	v_mfma_f32_16x16x32_bf16 v[124:127], v[154:157], v[186:189], v[124:127]
	v_mfma_f32_16x16x32_bf16 v[120:123], v[162:165], v[186:189], v[120:123]
	v_mfma_f32_16x16x32_bf16 v[116:119], v[154:157], v[194:197], v[116:119]
	v_mfma_f32_16x16x32_bf16 v[108:111], v[162:165], v[194:197], v[108:111]
	v_mfma_f32_16x16x32_bf16 v[100:103], v[154:157], v[202:205], v[100:103]
	v_mfma_f32_16x16x32_bf16 v[92:95], v[162:165], v[202:205], v[92:95]
	v_mfma_f32_16x16x32_bf16 v[84:87], v[154:157], v[210:213], v[84:87]
	v_mfma_f32_16x16x32_bf16 v[76:79], v[162:165], v[210:213], v[76:79]
	v_mfma_f32_16x16x32_bf16 v[124:127], v[158:161], v[190:193], v[124:127]
	v_mfma_f32_16x16x32_bf16 v[120:123], v[166:169], v[190:193], v[120:123]
	v_mfma_f32_16x16x32_bf16 v[116:119], v[158:161], v[198:201], v[116:119]
	v_mfma_f32_16x16x32_bf16 v[108:111], v[166:169], v[198:201], v[108:111]
	v_mfma_f32_16x16x32_bf16 v[100:103], v[158:161], v[206:209], v[100:103]
	v_mfma_f32_16x16x32_bf16 v[92:95], v[166:169], v[206:209], v[92:95]
	v_mfma_f32_16x16x32_bf16 v[84:87], v[158:161], v[214:217], v[84:87]
	v_mfma_f32_16x16x32_bf16 v[76:79], v[166:169], v[214:217], v[76:79]
	v_mfma_f32_16x16x32_bf16 v[112:115], v[170:173], v[186:189], v[112:115]
	v_mfma_f32_16x16x32_bf16 v[104:107], v[178:181], v[186:189], v[104:107]
	v_mfma_f32_16x16x32_bf16 v[96:99], v[170:173], v[194:197], v[96:99]
	v_mfma_f32_16x16x32_bf16 v[88:91], v[178:181], v[194:197], v[88:91]
	v_mfma_f32_16x16x32_bf16 v[80:83], v[170:173], v[202:205], v[80:83]
	v_mfma_f32_16x16x32_bf16 v[72:75], v[178:181], v[202:205], v[72:75]
	v_mfma_f32_16x16x32_bf16 v[68:71], v[170:173], v[210:213], v[68:71]
	v_mfma_f32_16x16x32_bf16 v[64:67], v[178:181], v[210:213], v[64:67]
	v_mfma_f32_16x16x32_bf16 v[112:115], v[174:177], v[190:193], v[112:115]
	v_mfma_f32_16x16x32_bf16 v[104:107], v[182:185], v[190:193], v[104:107]
	v_mfma_f32_16x16x32_bf16 v[96:99], v[174:177], v[198:201], v[96:99]
	v_mfma_f32_16x16x32_bf16 v[88:91], v[182:185], v[198:201], v[88:91]
	v_mfma_f32_16x16x32_bf16 v[80:83], v[174:177], v[206:209], v[80:83]
	v_mfma_f32_16x16x32_bf16 v[72:75], v[182:185], v[206:209], v[72:75]
	v_mfma_f32_16x16x32_bf16 v[68:71], v[174:177], v[214:217], v[68:71]
	v_mfma_f32_16x16x32_bf16 v[64:67], v[182:185], v[214:217], v[64:67]
	s_barrier
	s_add_i32 s52, s52, s3
	s_mov_b32 m0, s52
	ds_read_b128 v[186:189], v153 offset:49152
	ds_read_b128 v[190:193], v153 offset:50176
	ds_read_b128 v[194:197], v153 offset:51200
	ds_read_b128 v[198:201], v153 offset:52224
	ds_read_b128 v[202:205], v153 offset:53248
	ds_read_b128 v[206:209], v153 offset:54272
	ds_read_b128 v[210:213], v153 offset:55296
	ds_read_b128 v[214:217], v153 offset:56320
	s_add_u32 s98, s68, 0x80
	s_addc_u32 s99, s69, 0
	global_load_lds_dwordx4 v132, s[98:99]
	s_add_i32 m0, s52, 0x2000
	s_add_u32 s68, s68, 0x80080
	s_addc_u32 s69, s69, 0
	s_add_i32 s52, s53, s3
	global_load_lds_dwordx4 v128, s[98:99]
	s_mov_b32 m0, s52
	s_nop 0
	global_load_lds_dwordx4 v132, s[68:69]
	s_add_i32 m0, s52, 0x2000
	s_nop 0
	global_load_lds_dwordx4 v128, s[68:69]
	s_mov_b32 m0, s77
	s_nop 0
	s_add_u32 s100, s70, 0xfff80080
	s_addc_u32 s101, s71, -1
	global_load_lds_dwordx4 v134, s[100:101]
	s_mov_b32 m0, s78
	s_nop 0
	global_load_lds_dwordx4 v130, s[100:101]
	s_waitcnt vmcnt(8)
	s_waitcnt lgkmcnt(0)
	s_barrier
	s_waitcnt lgkmcnt(0)
	v_mfma_f32_16x16x32_bf16 v[60:63], v[154:157], v[186:189], v[60:63]
	v_mfma_f32_16x16x32_bf16 v[56:59], v[162:165], v[186:189], v[56:59]
	v_mfma_f32_16x16x32_bf16 v[52:55], v[154:157], v[194:197], v[52:55]
	v_mfma_f32_16x16x32_bf16 v[44:47], v[162:165], v[194:197], v[44:47]
	v_mfma_f32_16x16x32_bf16 v[36:39], v[154:157], v[202:205], v[36:39]
	v_mfma_f32_16x16x32_bf16 v[28:31], v[162:165], v[202:205], v[28:31]
	v_mfma_f32_16x16x32_bf16 v[20:23], v[154:157], v[210:213], v[20:23]
	v_mfma_f32_16x16x32_bf16 v[12:15], v[162:165], v[210:213], v[12:15]
	v_mfma_f32_16x16x32_bf16 v[60:63], v[158:161], v[190:193], v[60:63]
	v_mfma_f32_16x16x32_bf16 v[56:59], v[166:169], v[190:193], v[56:59]
	v_mfma_f32_16x16x32_bf16 v[52:55], v[158:161], v[198:201], v[52:55]
	v_mfma_f32_16x16x32_bf16 v[44:47], v[166:169], v[198:201], v[44:47]
	v_mfma_f32_16x16x32_bf16 v[36:39], v[158:161], v[206:209], v[36:39]
	v_mfma_f32_16x16x32_bf16 v[28:31], v[166:169], v[206:209], v[28:31]
	v_mfma_f32_16x16x32_bf16 v[20:23], v[158:161], v[214:217], v[20:23]
	v_mfma_f32_16x16x32_bf16 v[12:15], v[166:169], v[214:217], v[12:15]
	v_mfma_f32_16x16x32_bf16 v[48:51], v[170:173], v[186:189], v[48:51]
	v_mfma_f32_16x16x32_bf16 v[40:43], v[178:181], v[186:189], v[40:43]
	v_mfma_f32_16x16x32_bf16 v[32:35], v[170:173], v[194:197], v[32:35]
	v_mfma_f32_16x16x32_bf16 v[24:27], v[178:181], v[194:197], v[24:27]
	v_mfma_f32_16x16x32_bf16 v[16:19], v[170:173], v[202:205], v[16:19]
	v_mfma_f32_16x16x32_bf16 v[8:11], v[178:181], v[202:205], v[8:11]
	v_mfma_f32_16x16x32_bf16 v[4:7], v[170:173], v[210:213], v[4:7]
	v_mfma_f32_16x16x32_bf16 v[0:3], v[178:181], v[210:213], v[0:3]
	v_mfma_f32_16x16x32_bf16 v[48:51], v[174:177], v[190:193], v[48:51]
	v_mfma_f32_16x16x32_bf16 v[40:43], v[182:185], v[190:193], v[40:43]
	v_mfma_f32_16x16x32_bf16 v[32:35], v[174:177], v[198:201], v[32:35]
	v_mfma_f32_16x16x32_bf16 v[24:27], v[182:185], v[198:201], v[24:27]
	v_mfma_f32_16x16x32_bf16 v[16:19], v[174:177], v[206:209], v[16:19]
	v_mfma_f32_16x16x32_bf16 v[8:11], v[182:185], v[206:209], v[8:11]
	v_mfma_f32_16x16x32_bf16 v[4:7], v[174:177], v[214:217], v[4:7]
	v_mfma_f32_16x16x32_bf16 v[0:3], v[182:185], v[214:217], v[0:3]
	s_barrier
	s_add_i32 s91, s91, 2
	s_add_u32 s54, s54, 0x100
	s_addc_u32 s55, s55, 0
	s_add_u32 s89, s89, 0x100
	s_addc_u32 s90, s90, 0
	s_cmp_gt_u32 s91, 29
	s_cbranch_scc0 .LBB0_61
	s_and_b64 vcc, exec, s[10:11]
	s_cbranch_vccz .LBB0_64
	s_barrier

; #define PG8_WAIT_V(n) asm volatile("s_waitcnt vmcnt(" #n ")" ::: "memory")
; #define PG8_BAR __builtin_amdgcn_s_barrier()
; template <class Epi, class Sched, bool ALIGN_EPI = false, bool SP2 = false>
; __device__ __forceinline__ void gemm_phase(PG8_LAS unsigned char* lds, const Gemm g, const Sched& S, const Epi& E) {
;     ...
;     PG8_WAIT_V(0);
;     if constexpr (!ALIGN_EPI) { if (wr == 0) PG8_BAR; }
;     PG8_BAR;
.LBB0_67:
	s_setprio 0
	s_waitcnt vmcnt(0)
	v_readlane_b32 s52, v255, 0
	v_readlane_b32 s53, v255, 1
	s_barrier
	v_readlane_b32 s54, v255, 2
	v_readlane_b32 s55, v255, 3
	v_readlane_b32 s56, v255, 4
	v_readlane_b32 s57, v255, 5
	v_readlane_b32 s58, v255, 6
	v_readlane_b32 s59, v255, 7
	v_readlane_b32 s60, v255, 8
	v_readlane_b32 s61, v255, 9
	v_readlane_b32 s62, v255, 10
	v_readlane_b32 s63, v255, 11
	v_readlane_b32 s64, v255, 12
	v_readlane_b32 s65, v255, 13
	v_readlane_b32 s66, v255, 14
	v_readlane_b32 s67, v255, 15

; #define PG8_STAGE(bufoff, gbase, voff) do { _Pragma("unroll") for (int _i = 0; _i < 2; ++_i) \
;         __builtin_amdgcn_global_load_lds((const unsigned*)((const char*)(gbase) + (voff)[_i]), (PG8_LAS unsigned*)(lds + (bufoff) + ldsw + _i * 8192), 16, 0, 0); } while (0)
; #define PG8_WAIT_V(n) asm volatile("s_waitcnt vmcnt(" #n ")" ::: "memory")
; #define PG8_BAR __builtin_amdgcn_s_barrier()
; template <class Epi, class Sched, bool ALIGN_EPI = false, bool SP2 = false>
; __device__ __forceinline__ void gemm_phase(PG8_LAS unsigned char* lds, const Gemm g, const Sched& S, const Epi& E) {
;     ...
;     for (int i = 0; i < 2; ++i) { int R, C; stage_rc(tid * 16 + i * 8192, R, C); const int Rb = Epi::PERM ? ((R & ~31) + perm32(R & 31)) : R;
;         voffA[i] = (unsigned)(R * K + C) * 2u; voffB[i] = (unsigned)(Rb * K + C) * 2u; }
;     const size_t kstep = (size_t)(BK * 2);
;     const size_t hstep = (size_t)HALF * K * 2;
;     const size_t tstep = 2 * hstep;
;     const unsigned ldsw = (unsigned)wid * 1024u;
;     const int aoff = lds_byte(wr * 64 + fr, fq * 8), boff = lds_byte(wc * 32 + fr, fq * 8);
;     ...
;         PG8_STAGE(PG8_SB(0, 0), cB, voffB); PG8_STAGE(PG8_SB(0, 1), cB + hstep, voffB); PG8_STAGE(PG8_SA(0, 0), cA, voffA); PG8_STAGE(PG8_SA(0, 1), cA + hstep, voffA);
;         if (wr == 1) PG8_BAR;
;         PG8_WAIT_V(2); PG8_BAR;
;         PG8_STAGE(PG8_SB(1, 0), cB + kstep, voffB); PG8_STAGE(PG8_SA(1, 0), cA + kstep, voffA); PG8_STAGE(PG8_SB(1, 1), cB + hstep + kstep, voffB);
;         PG8_WAIT_V(6); PG8_BAR;
.LBB0_654:
	s_add_u32 s10, s34, 0x1c000000
	s_addc_u32 s11, s35, 0
	s_add_u32 s12, s34, 0x7e00000
	s_addc_u32 s13, s35, 0
	s_lshl_b32 s1, s1, 5
	s_mov_b64 s[14:15], 0x80
	s_and_b32 s18, s1, 0x60
	s_add_i32 m0, s41, 0x18000
	v_lshl_add_u64 v[6:7], v[6:7], 0, s[14:15]
	s_lshl_b32 s17, s0, 13
	s_lshl_b32 s1, s18, 7
	s_waitcnt vmcnt(2)
	s_barrier
	global_load_lds_dwordx4 v[6:7], off
	v_lshl_add_u64 v[4:5], v[4:5], 0, s[14:15]
	s_add_i32 m0, s41, 0x1a000
	s_add_i32 s54, s41, 0x8000
	s_add_i32 s55, s41, 0xa000
	global_load_lds_dwordx4 v[4:5], off
	v_lshl_add_u64 v[0:1], v[0:1], 0, s[14:15]
	s_mov_b32 m0, s54
	s_add_u32 s4, s44, 0x80080
	global_load_lds_dwordx4 v[0:1], off
	v_lshl_add_u64 v[0:1], v[2:3], 0, s[14:15]
	s_mov_b32 m0, s55
	s_addc_u32 s5, s45, 0
	global_load_lds_dwordx4 v[0:1], off
	s_add_i32 m0, s41, 0x1c000
	v_lshl_add_u64 v[0:1], s[4:5], 0, v[130:131]
	global_load_lds_dwordx4 v[0:1], off
	v_lshl_add_u64 v[0:1], s[4:5], 0, v[134:135]
	s_add_i32 m0, s41, 0x1e000
	v_lshlrev_b32_e32 v3, 2, v220
	global_load_lds_dwordx4 v[0:1], off
	v_and_b32_e32 v0, 15, v220
	v_bfe_u32 v1, v220, 4, 2
	v_lshl_or_b32 v150, s0, 6, v0
	v_lshlrev_b32_e32 v2, 4, v1
	v_lshlrev_b32_e32 v4, 6, v220
	s_movk_i32 s0, 0x3c0
	v_lshl_or_b32 v0, v0, 6, v2
	v_and_b32_e32 v3, 32, v3
	v_and_or_b32 v2, v4, s0, v2
	v_bitop3_b32 v151, s1, v2, v3 bitop3:0xf6
	v_cmp_eq_u32_e64 s[0:1], 0, v1
	v_lshl_or_b32 v152, v1, 3, s18
	v_lshlrev_b32_e32 v1, 9, v220
	v_and_b32_e32 v1, 0x70000, v1
	v_lshlrev_b32_e32 v2, 12, v10
	v_or3_b32 v1, v8, v1, v2
	v_add_u32_e32 v136, v1, v9
	v_lshlrev_b32_e32 v1, 5, v11
	v_bitop3_b32 v0, v0, s17, v3 bitop3:0xde
	s_waitcnt vmcnt(6)
	s_cmpk_lt_u32 s16, 0x100
	v_and_b32_e32 v1, 0xf0000, v1
	s_cselect_b64 s[16:17], -1, 0
	v_or3_b32 v1, v8, v1, v2
	s_add_i32 s58, 0, 0x10000
	s_add_i32 s59, 0, 0x14000
	v_add_u32_e32 v155, 0, v0
	v_mbcnt_lo_u32_b32 v0, -1, 0
	s_waitcnt lgkmcnt(0)
	s_ashr_i32 s56, s33, 31
	s_ashr_i32 s57, s2, 31
	v_mov_b32_e32 v137, v131
	v_add_u32_e32 v138, v1, v9
	v_mov_b32_e32 v139, v131
	v_mov_b64_e32 v[140:141], 0x400
	v_mov_b64_e32 v[142:143], 0x3ff
	v_add_u32_e32 v153, s58, v151
	v_add_u32_e32 v154, s59, v151
	v_mbcnt_hi_u32_b32 v156, -1, v0
	s_barrier
	v_readfirstlane_b32 s101, v220
	s_nop 3
	s_lshr_b32 s101, s101, 6
	s_cmp_lt_u32 s101, 4
	s_cbranch_scc0 .Lprio_skip_1
	s_setprio 1

; #define PG8_STAGE(bufoff, gbase, voff) do { _Pragma("unroll") for (int _i = 0; _i < 2; ++_i) \
;         __builtin_amdgcn_global_load_lds((const unsigned*)((const char*)(gbase) + (voff)[_i]), (PG8_LAS unsigned*)(lds + (bufoff) + ldsw + _i * 8192), 16, 0, 0); } while (0)
; #define PG8_LDA(dst, b, h) do { _Pragma("unroll") for (int m = 0; m < 4; ++m) _Pragma("unroll") for (int k = 0; k < 2; ++k) dst[m][k] = *(const PG8_LAS bf16x8*)(lds + PG8_SA(b, h) + aoff + m * 2048 + k * 1024); } while (0)
; #define PG8_LDB(dst, b, h) do { _Pragma("unroll") for (int n = 0; n < 2; ++n) _Pragma("unroll") for (int k = 0; k < 2; ++k) dst[n][k] = *(const PG8_LAS bf16x8*)(lds + PG8_SB(b, h) + boff + n * 2048 + k * 1024); } while (0)
; #define PG8_MMA(ai, bj, At, Bt) do { __builtin_amdgcn_s_setprio(1); _Pragma("unroll") for (int m = 0; m < 4; ++m) _Pragma("unroll") for (int n = 0; n < 2; ++n) _Pragma("unroll") for (int k = 0; k < 2; ++k) \
;         acc[ai][bj][m][n] = __builtin_amdgcn_mfma_f32_16x16x32_bf16(Bt[n][k], At[m][k], acc[ai][bj][m][n], 0, 0, 0); __builtin_amdgcn_s_setprio(0); } while (0)
; #define PG8_WAIT_V(n) asm volatile("s_waitcnt vmcnt(" #n ")" ::: "memory")
; #define PG8_WAIT_L(n) asm volatile("s_waitcnt lgkmcnt(" #n ")" ::: "memory")
; #define PG8_BAR __builtin_amdgcn_s_barrier()
; #define PG8_SCHED __builtin_amdgcn_sched_barrier(0)
; template <class Epi, class Sched, bool ALIGN_EPI = false, bool SP2 = false>
; __device__ __forceinline__ void gemm_phase(PG8_LAS unsigned char* lds, const Gemm g, const Sched& S, const Epi& E) {
;     ...
;             PG8_LDB(B0, 0, 0); PG8_LDB(B1, 0, 1); PG8_SCHED; PG8_LDA(At, 0, 0); PG8_STAGE(PG8_SA(1, 1), a1 + hstep, voffA);
;             PG8_WAIT_V(8); PG8_WAIT_L(0); PG8_BAR; PG8_MMA(0, 0, At, B0); PG8_MMA(0, 1, At, B1); PG8_BAR; PG8_SCHED;
;             PG8_LDA(At, 0, 1); PG8_STAGE(PG8_SB(0, 0), b2, voffB); PG8_STAGE(PG8_SB(0, 1), b2 + hstep, voffB); PG8_STAGE(PG8_SA(0, 0), a2, voffA);
;             PG8_WAIT_V(8); PG8_WAIT_L(0); PG8_BAR; PG8_MMA(1, 0, At, B0); PG8_MMA(1, 1, At, B1); PG8_BAR; PG8_SCHED;
.LBB0_664:
	ds_read_b128 v[144:147], v153
	ds_read_b128 v[158:161], v153 offset:1024
	ds_read_b128 v[162:165], v153 offset:2048
	ds_read_b128 v[166:169], v153 offset:3072
	ds_read_b128 v[170:173], v154
	ds_read_b128 v[174:177], v154 offset:1024
	ds_read_b128 v[178:181], v154 offset:2048
	ds_read_b128 v[182:185], v154 offset:3072
	s_add_u32 s44, s42, 0xfff80080
	s_addc_u32 s45, s43, -1
	s_cmp_eq_u32 s63, 28
	s_cselect_b32 s47, s21, s45
	s_cselect_b32 s46, s31, s44
	s_cselect_b32 s45, s19, s62
	s_cselect_b32 s44, s60, s61
	s_add_i32 m0, s41, 0xc000
	ds_read_b128 v[186:189], v155
	ds_read_b128 v[190:193], v155 offset:1024
	ds_read_b128 v[194:197], v155 offset:2048
	ds_read_b128 v[198:201], v155 offset:3072
	ds_read_b128 v[202:205], v155 offset:4096
	ds_read_b128 v[206:209], v155 offset:5120
	ds_read_b128 v[210:213], v155 offset:6144
	ds_read_b128 v[214:217], v155 offset:7168
	global_load_lds_dwordx4 v136, s[42:43]
	s_add_i32 m0, s41, 0xe000
	s_nop 0
	global_load_lds_dwordx4 v138, s[42:43]
	s_waitcnt vmcnt(8)
	s_waitcnt lgkmcnt(0)
	s_barrier
	s_waitcnt lgkmcnt(0)
	v_mfma_f32_16x16x32_bf16 v[124:127], v[144:147], v[186:189], v[124:127]
	v_mfma_f32_16x16x32_bf16 v[120:123], v[162:165], v[186:189], v[120:123]
	v_mfma_f32_16x16x32_bf16 v[108:111], v[144:147], v[194:197], v[108:111]
	v_mfma_f32_16x16x32_bf16 v[104:107], v[162:165], v[194:197], v[104:107]
	v_mfma_f32_16x16x32_bf16 v[92:95], v[144:147], v[202:205], v[92:95]
	v_mfma_f32_16x16x32_bf16 v[88:91], v[162:165], v[202:205], v[88:91]
	v_mfma_f32_16x16x32_bf16 v[76:79], v[144:147], v[210:213], v[76:79]
	v_mfma_f32_16x16x32_bf16 v[72:75], v[162:165], v[210:213], v[72:75]
	v_mfma_f32_16x16x32_bf16 v[124:127], v[158:161], v[190:193], v[124:127]
	v_mfma_f32_16x16x32_bf16 v[120:123], v[166:169], v[190:193], v[120:123]
	v_mfma_f32_16x16x32_bf16 v[108:111], v[158:161], v[198:201], v[108:111]
	v_mfma_f32_16x16x32_bf16 v[104:107], v[166:169], v[198:201], v[104:107]
	v_mfma_f32_16x16x32_bf16 v[92:95], v[158:161], v[206:209], v[92:95]
	v_mfma_f32_16x16x32_bf16 v[88:91], v[166:169], v[206:209], v[88:91]
	v_mfma_f32_16x16x32_bf16 v[76:79], v[158:161], v[214:217], v[76:79]
	v_mfma_f32_16x16x32_bf16 v[72:75], v[166:169], v[214:217], v[72:75]
	v_mfma_f32_16x16x32_bf16 v[116:119], v[170:173], v[186:189], v[116:119]
	v_mfma_f32_16x16x32_bf16 v[112:115], v[178:181], v[186:189], v[112:115]
	v_mfma_f32_16x16x32_bf16 v[100:103], v[170:173], v[194:197], v[100:103]
	v_mfma_f32_16x16x32_bf16 v[96:99], v[178:181], v[194:197], v[96:99]
	v_mfma_f32_16x16x32_bf16 v[84:87], v[170:173], v[202:205], v[84:87]
	v_mfma_f32_16x16x32_bf16 v[80:83], v[178:181], v[202:205], v[80:83]
	v_mfma_f32_16x16x32_bf16 v[68:71], v[170:173], v[210:213], v[68:71]
	v_mfma_f32_16x16x32_bf16 v[64:67], v[178:181], v[210:213], v[64:67]
	v_mfma_f32_16x16x32_bf16 v[116:119], v[174:177], v[190:193], v[116:119]
	v_mfma_f32_16x16x32_bf16 v[112:115], v[182:185], v[190:193], v[112:115]
	v_mfma_f32_16x16x32_bf16 v[100:103], v[174:177], v[198:201], v[100:103]
	v_mfma_f32_16x16x32_bf16 v[96:99], v[182:185], v[198:201], v[96:99]
	v_mfma_f32_16x16x32_bf16 v[84:87], v[174:177], v[206:209], v[84:87]
	v_mfma_f32_16x16x32_bf16 v[80:83], v[182:185], v[206:209], v[80:83]
	v_mfma_f32_16x16x32_bf16 v[68:71], v[174:177], v[214:217], v[68:71]
	v_mfma_f32_16x16x32_bf16 v[64:67], v[182:185], v[214:217], v[64:67]
	s_barrier
	s_add_i32 s64, s58, s49
	s_mov_b32 m0, s64
	ds_read_b128 v[186:189], v155 offset:16384
	ds_read_b128 v[190:193], v155 offset:17408
	ds_read_b128 v[194:197], v155 offset:18432
	ds_read_b128 v[198:201], v155 offset:19456
	ds_read_b128 v[202:205], v155 offset:20480
	ds_read_b128 v[206:209], v155 offset:21504
	ds_read_b128 v[210:213], v155 offset:22528
	ds_read_b128 v[214:217], v155 offset:23552
	global_load_lds_dwordx4 v130, s[44:45]
	s_add_i32 m0, s64, 0x2000
	s_add_u32 s64, s44, 0x80000
	s_addc_u32 s65, s45, 0
	s_add_i32 s66, s59, s49
	global_load_lds_dwordx4 v134, s[44:45]
	s_mov_b32 m0, s66
	s_nop 0
	global_load_lds_dwordx4 v130, s[64:65]
	s_add_i32 m0, s66, 0x2000
	s_nop 0
	global_load_lds_dwordx4 v134, s[64:65]
	s_mov_b32 m0, s41
	s_nop 0
	global_load_lds_dwordx4 v128, s[46:47]
	s_mov_b32 m0, s50
	s_nop 0
	global_load_lds_dwordx4 v132, s[46:47]
	s_waitcnt vmcnt(8)
	s_waitcnt lgkmcnt(0)
	s_barrier
	s_waitcnt lgkmcnt(0)
	v_mfma_f32_16x16x32_bf16 v[60:63], v[144:147], v[186:189], v[60:63]
	v_mfma_f32_16x16x32_bf16 v[56:59], v[162:165], v[186:189], v[56:59]
	v_mfma_f32_16x16x32_bf16 v[44:47], v[144:147], v[194:197], v[44:47]
	v_mfma_f32_16x16x32_bf16 v[40:43], v[162:165], v[194:197], v[40:43]
	v_mfma_f32_16x16x32_bf16 v[28:31], v[144:147], v[202:205], v[28:31]
	v_mfma_f32_16x16x32_bf16 v[24:27], v[162:165], v[202:205], v[24:27]
	v_mfma_f32_16x16x32_bf16 v[12:15], v[144:147], v[210:213], v[12:15]
	v_mfma_f32_16x16x32_bf16 v[8:11], v[162:165], v[210:213], v[8:11]
	v_mfma_f32_16x16x32_bf16 v[60:63], v[158:161], v[190:193], v[60:63]
	v_mfma_f32_16x16x32_bf16 v[56:59], v[166:169], v[190:193], v[56:59]
	v_mfma_f32_16x16x32_bf16 v[44:47], v[158:161], v[198:201], v[44:47]
	v_mfma_f32_16x16x32_bf16 v[40:43], v[166:169], v[198:201], v[40:43]
	v_mfma_f32_16x16x32_bf16 v[28:31], v[158:161], v[206:209], v[28:31]
	v_mfma_f32_16x16x32_bf16 v[24:27], v[166:169], v[206:209], v[24:27]
	v_mfma_f32_16x16x32_bf16 v[12:15], v[158:161], v[214:217], v[12:15]
	v_mfma_f32_16x16x32_bf16 v[8:11], v[166:169], v[214:217], v[8:11]
	v_mfma_f32_16x16x32_bf16 v[52:55], v[170:173], v[186:189], v[52:55]
	v_mfma_f32_16x16x32_bf16 v[48:51], v[178:181], v[186:189], v[48:51]
	v_mfma_f32_16x16x32_bf16 v[36:39], v[170:173], v[194:197], v[36:39]
	v_mfma_f32_16x16x32_bf16 v[32:35], v[178:181], v[194:197], v[32:35]
	v_mfma_f32_16x16x32_bf16 v[20:23], v[170:173], v[202:205], v[20:23]
	v_mfma_f32_16x16x32_bf16 v[16:19], v[178:181], v[202:205], v[16:19]
	v_mfma_f32_16x16x32_bf16 v[4:7], v[170:173], v[210:213], v[4:7]
	v_mfma_f32_16x16x32_bf16 v[0:3], v[178:181], v[210:213], v[0:3]
	v_mfma_f32_16x16x32_bf16 v[52:55], v[174:177], v[190:193], v[52:55]
	v_mfma_f32_16x16x32_bf16 v[48:51], v[182:185], v[190:193], v[48:51]
	v_mfma_f32_16x16x32_bf16 v[36:39], v[174:177], v[198:201], v[36:39]
	v_mfma_f32_16x16x32_bf16 v[32:35], v[182:185], v[198:201], v[32:35]
	v_mfma_f32_16x16x32_bf16 v[20:23], v[174:177], v[206:209], v[20:23]
	v_mfma_f32_16x16x32_bf16 v[16:19], v[182:185], v[206:209], v[16:19]
	v_mfma_f32_16x16x32_bf16 v[4:7], v[174:177], v[214:217], v[4:7]
	v_mfma_f32_16x16x32_bf16 v[0:3], v[182:185], v[214:217], v[0:3]
	s_barrier
; #define PG8_STAGE(bufoff, gbase, voff) do { _Pragma("unroll") for (int _i = 0; _i < 2; ++_i) \
;         __builtin_amdgcn_global_load_lds((const unsigned*)((const char*)(gbase) + (voff)[_i]), (PG8_LAS unsigned*)(lds + (bufoff) + ldsw + _i * 8192), 16, 0, 0); } while (0)
; #define PG8_LDA(dst, b, h) do { _Pragma("unroll") for (int m = 0; m < 4; ++m) _Pragma("unroll") for (int k = 0; k < 2; ++k) dst[m][k] = *(const PG8_LAS bf16x8*)(lds + PG8_SA(b, h) + aoff + m * 2048 + k * 1024); } while (0)
; #define PG8_LDB(dst, b, h) do { _Pragma("unroll") for (int n = 0; n < 2; ++n) _Pragma("unroll") for (int k = 0; k < 2; ++k) dst[n][k] = *(const PG8_LAS bf16x8*)(lds + PG8_SB(b, h) + boff + n * 2048 + k * 1024); } while (0)
; #define PG8_MMA(ai, bj, At, Bt) do { __builtin_amdgcn_s_setprio(1); _Pragma("unroll") for (int m = 0; m < 4; ++m) _Pragma("unroll") for (int n = 0; n < 2; ++n) _Pragma("unroll") for (int k = 0; k < 2; ++k) \
;         acc[ai][bj][m][n] = __builtin_amdgcn_mfma_f32_16x16x32_bf16(Bt[n][k], At[m][k], acc[ai][bj][m][n], 0, 0, 0); __builtin_amdgcn_s_setprio(0); } while (0)
; #define PG8_WAIT_V(n) asm volatile("s_waitcnt vmcnt(" #n ")" ::: "memory")
; #define PG8_WAIT_L(n) asm volatile("s_waitcnt lgkmcnt(" #n ")" ::: "memory")
; #define PG8_BAR __builtin_amdgcn_s_barrier()
; #define PG8_SCHED __builtin_amdgcn_sched_barrier(0)
; template <class Epi, class Sched, bool ALIGN_EPI = false, bool SP2 = false>
; __device__ __forceinline__ void gemm_phase(PG8_LAS unsigned char* lds, const Gemm g, const Sched& S, const Epi& E) {
;     ...
;             PG8_LDB(B0, 1, 0); PG8_LDB(B1, 1, 1); PG8_SCHED; PG8_LDA(At, 1, 0); PG8_STAGE(PG8_SA(0, 1), a2 + hstep, voffA);
;             PG8_WAIT_V(8); PG8_WAIT_L(0); PG8_BAR; PG8_MMA(0, 0, At, B0); PG8_MMA(0, 1, At, B1); PG8_BAR; PG8_SCHED;
;             PG8_LDA(At, 1, 1); PG8_STAGE(PG8_SB(1, 0), b3, voffB); PG8_STAGE(PG8_SB(1, 1), b3 + hstep, voffB); PG8_STAGE(PG8_SA(1, 0), a3, voffA);
;             PG8_WAIT_V(8); PG8_WAIT_L(0); PG8_BAR; PG8_MMA(1, 0, At, B0); PG8_MMA(1, 1, At, B1); PG8_BAR; PG8_SCHED;
	s_add_i32 s64, 0, 0x18000
	v_add_u32_e32 v157, s64, v151
	s_add_i32 s65, 0, 0x1c000
	ds_read_b128 v[144:147], v157
	ds_read_b128 v[158:161], v157 offset:1024
	ds_read_b128 v[162:165], v157 offset:2048
	ds_read_b128 v[166:169], v157 offset:3072
	v_add_u32_e32 v157, s65, v151
	ds_read_b128 v[170:173], v157
	ds_read_b128 v[174:177], v157 offset:1024
	ds_read_b128 v[178:181], v157 offset:2048
	ds_read_b128 v[182:185], v157 offset:3072
	s_add_u32 s46, s46, 0x80000
	s_addc_u32 s47, s47, 0
	s_mov_b32 m0, s51
	ds_read_b128 v[186:189], v155 offset:32768
	ds_read_b128 v[190:193], v155 offset:33792
	ds_read_b128 v[194:197], v155 offset:34816
	ds_read_b128 v[198:201], v155 offset:35840
	ds_read_b128 v[202:205], v155 offset:36864
	ds_read_b128 v[206:209], v155 offset:37888
	ds_read_b128 v[210:213], v155 offset:38912
	ds_read_b128 v[214:217], v155 offset:39936
	global_load_lds_dwordx4 v128, s[46:47]
	s_mov_b32 m0, s52
	s_nop 0
	global_load_lds_dwordx4 v132, s[46:47]
	s_waitcnt vmcnt(8)
	s_waitcnt lgkmcnt(0)
	s_barrier
	s_waitcnt lgkmcnt(0)
	v_mfma_f32_16x16x32_bf16 v[124:127], v[144:147], v[186:189], v[124:127]
	v_mfma_f32_16x16x32_bf16 v[120:123], v[162:165], v[186:189], v[120:123]
	v_mfma_f32_16x16x32_bf16 v[108:111], v[144:147], v[194:197], v[108:111]
	v_mfma_f32_16x16x32_bf16 v[104:107], v[162:165], v[194:197], v[104:107]
	v_mfma_f32_16x16x32_bf16 v[92:95], v[144:147], v[202:205], v[92:95]
	v_mfma_f32_16x16x32_bf16 v[88:91], v[162:165], v[202:205], v[88:91]
	v_mfma_f32_16x16x32_bf16 v[76:79], v[144:147], v[210:213], v[76:79]
	v_mfma_f32_16x16x32_bf16 v[72:75], v[162:165], v[210:213], v[72:75]
	v_mfma_f32_16x16x32_bf16 v[124:127], v[158:161], v[190:193], v[124:127]
	v_mfma_f32_16x16x32_bf16 v[120:123], v[166:169], v[190:193], v[120:123]
	v_mfma_f32_16x16x32_bf16 v[108:111], v[158:161], v[198:201], v[108:111]
	v_mfma_f32_16x16x32_bf16 v[104:107], v[166:169], v[198:201], v[104:107]
	v_mfma_f32_16x16x32_bf16 v[92:95], v[158:161], v[206:209], v[92:95]
	v_mfma_f32_16x16x32_bf16 v[88:91], v[166:169], v[206:209], v[88:91]
	v_mfma_f32_16x16x32_bf16 v[76:79], v[158:161], v[214:217], v[76:79]
	v_mfma_f32_16x16x32_bf16 v[72:75], v[166:169], v[214:217], v[72:75]
	v_mfma_f32_16x16x32_bf16 v[116:119], v[170:173], v[186:189], v[116:119]
	v_mfma_f32_16x16x32_bf16 v[112:115], v[178:181], v[186:189], v[112:115]
	v_mfma_f32_16x16x32_bf16 v[100:103], v[170:173], v[194:197], v[100:103]
	v_mfma_f32_16x16x32_bf16 v[96:99], v[178:181], v[194:197], v[96:99]
	v_mfma_f32_16x16x32_bf16 v[84:87], v[170:173], v[202:205], v[84:87]
	v_mfma_f32_16x16x32_bf16 v[80:83], v[178:181], v[202:205], v[80:83]
	v_mfma_f32_16x16x32_bf16 v[68:71], v[170:173], v[210:213], v[68:71]
	v_mfma_f32_16x16x32_bf16 v[64:67], v[178:181], v[210:213], v[64:67]
	v_mfma_f32_16x16x32_bf16 v[116:119], v[174:177], v[190:193], v[116:119]
	v_mfma_f32_16x16x32_bf16 v[112:115], v[182:185], v[190:193], v[112:115]
	v_mfma_f32_16x16x32_bf16 v[100:103], v[174:177], v[198:201], v[100:103]
	v_mfma_f32_16x16x32_bf16 v[96:99], v[182:185], v[198:201], v[96:99]
	v_mfma_f32_16x16x32_bf16 v[84:87], v[174:177], v[206:209], v[84:87]
	v_mfma_f32_16x16x32_bf16 v[80:83], v[182:185], v[206:209], v[80:83]
	v_mfma_f32_16x16x32_bf16 v[68:71], v[174:177], v[214:217], v[68:71]
	v_mfma_f32_16x16x32_bf16 v[64:67], v[182:185], v[214:217], v[64:67]
	s_barrier
	s_mov_b64 s[68:69], s[46:47]
	s_add_i32 s46, s64, s49
	s_mov_b32 m0, s46
	ds_read_b128 v[186:189], v155 offset:49152
	ds_read_b128 v[190:193], v155 offset:50176
	ds_read_b128 v[194:197], v155 offset:51200
	ds_read_b128 v[198:201], v155 offset:52224
	ds_read_b128 v[202:205], v155 offset:53248
	ds_read_b128 v[206:209], v155 offset:54272
	ds_read_b128 v[210:213], v155 offset:55296
	ds_read_b128 v[214:217], v155 offset:56320
	s_add_u32 s70, s44, 0x80
	s_addc_u32 s71, s45, 0
	global_load_lds_dwordx4 v130, s[70:71]
	s_add_i32 m0, s46, 0x2000
	s_add_u32 s44, s44, 0x80080
	s_addc_u32 s45, s45, 0
	s_add_i32 s46, s65, s49
	global_load_lds_dwordx4 v134, s[70:71]
	s_mov_b32 m0, s46
	s_nop 0
	global_load_lds_dwordx4 v130, s[44:45]
	s_add_i32 m0, s46, 0x2000
	s_nop 0
	global_load_lds_dwordx4 v134, s[44:45]
	s_mov_b32 m0, s54
	s_nop 0
	s_add_u32 s72, s68, 0xfff80080
	s_addc_u32 s73, s69, -1
	global_load_lds_dwordx4 v128, s[72:73]
	s_mov_b32 m0, s55
	s_nop 0
	global_load_lds_dwordx4 v132, s[72:73]
	s_waitcnt vmcnt(8)
	s_waitcnt lgkmcnt(0)
	s_barrier
	s_waitcnt lgkmcnt(0)
	v_mfma_f32_16x16x32_bf16 v[60:63], v[144:147], v[186:189], v[60:63]
	v_mfma_f32_16x16x32_bf16 v[56:59], v[162:165], v[186:189], v[56:59]
	v_mfma_f32_16x16x32_bf16 v[44:47], v[144:147], v[194:197], v[44:47]
	v_mfma_f32_16x16x32_bf16 v[40:43], v[162:165], v[194:197], v[40:43]
	v_mfma_f32_16x16x32_bf16 v[28:31], v[144:147], v[202:205], v[28:31]
	v_mfma_f32_16x16x32_bf16 v[24:27], v[162:165], v[202:205], v[24:27]
	v_mfma_f32_16x16x32_bf16 v[12:15], v[144:147], v[210:213], v[12:15]
	v_mfma_f32_16x16x32_bf16 v[8:11], v[162:165], v[210:213], v[8:11]
	v_mfma_f32_16x16x32_bf16 v[60:63], v[158:161], v[190:193], v[60:63]
	v_mfma_f32_16x16x32_bf16 v[56:59], v[166:169], v[190:193], v[56:59]
	v_mfma_f32_16x16x32_bf16 v[44:47], v[158:161], v[198:201], v[44:47]
	v_mfma_f32_16x16x32_bf16 v[40:43], v[166:169], v[198:201], v[40:43]
	v_mfma_f32_16x16x32_bf16 v[28:31], v[158:161], v[206:209], v[28:31]
	v_mfma_f32_16x16x32_bf16 v[24:27], v[166:169], v[206:209], v[24:27]
	v_mfma_f32_16x16x32_bf16 v[12:15], v[158:161], v[214:217], v[12:15]
	v_mfma_f32_16x16x32_bf16 v[8:11], v[166:169], v[214:217], v[8:11]
	v_mfma_f32_16x16x32_bf16 v[52:55], v[170:173], v[186:189], v[52:55]
	v_mfma_f32_16x16x32_bf16 v[48:51], v[178:181], v[186:189], v[48:51]
	v_mfma_f32_16x16x32_bf16 v[36:39], v[170:173], v[194:197], v[36:39]
	v_mfma_f32_16x16x32_bf16 v[32:35], v[178:181], v[194:197], v[32:35]
	v_mfma_f32_16x16x32_bf16 v[20:23], v[170:173], v[202:205], v[20:23]
	v_mfma_f32_16x16x32_bf16 v[16:19], v[178:181], v[202:205], v[16:19]
	v_mfma_f32_16x16x32_bf16 v[4:7], v[170:173], v[210:213], v[4:7]
	v_mfma_f32_16x16x32_bf16 v[0:3], v[178:181], v[210:213], v[0:3]
	v_mfma_f32_16x16x32_bf16 v[52:55], v[174:177], v[190:193], v[52:55]
	v_mfma_f32_16x16x32_bf16 v[48:51], v[182:185], v[190:193], v[48:51]
	v_mfma_f32_16x16x32_bf16 v[36:39], v[174:177], v[198:201], v[36:39]
	v_mfma_f32_16x16x32_bf16 v[32:35], v[182:185], v[198:201], v[32:35]
	v_mfma_f32_16x16x32_bf16 v[20:23], v[174:177], v[206:209], v[20:23]
	v_mfma_f32_16x16x32_bf16 v[16:19], v[182:185], v[206:209], v[16:19]
	v_mfma_f32_16x16x32_bf16 v[4:7], v[174:177], v[214:217], v[4:7]
	v_mfma_f32_16x16x32_bf16 v[0:3], v[182:185], v[214:217], v[0:3]
	s_barrier
	s_add_i32 s63, s63, 2
	s_add_u32 s42, s42, 0x100
	s_addc_u32 s43, s43, 0
	s_add_u32 s61, s61, 0x100
	s_addc_u32 s62, s62, 0
	s_cmp_gt_u32 s63, 29
	s_cbranch_scc0 .LBB0_664
	s_and_b64 vcc, exec, s[16:17]
	s_cbranch_vccz .LBB0_667
	s_barrier

; #define PG8_WAIT_V(n) asm volatile("s_waitcnt vmcnt(" #n ")" ::: "memory")
; #define PG8_BAR __builtin_amdgcn_s_barrier()
; template <class Epi, class Sched, bool ALIGN_EPI = false, bool SP2 = false>
; __device__ __forceinline__ void gemm_phase(PG8_LAS unsigned char* lds, const Gemm g, const Sched& S, const Epi& E) {
;     ...
;     PG8_WAIT_V(0);
;     if constexpr (!ALIGN_EPI) { if (wr == 0) PG8_BAR; }
;     PG8_BAR;
.LBB0_686:
	s_setprio 0
	s_waitcnt vmcnt(0)
	s_barrier

; #define PG8_STAGE(bufoff, gbase, voff) do { _Pragma("unroll") for (int _i = 0; _i < 2; ++_i) \
;         __builtin_amdgcn_global_load_lds((const unsigned*)((const char*)(gbase) + (voff)[_i]), (PG8_LAS unsigned*)(lds + (bufoff) + ldsw + _i * 8192), 16, 0, 0); } while (0)
; #define PG8_WAIT_V(n) asm volatile("s_waitcnt vmcnt(" #n ")" ::: "memory")
; #define PG8_BAR __builtin_amdgcn_s_barrier()
; template <class Epi, class Sched, bool ALIGN_EPI = false, bool SP2 = false>
; __device__ __forceinline__ void gemm_phase(PG8_LAS unsigned char* lds, const Gemm g, const Sched& S, const Epi& E) {
;     ...
;     for (int i = 0; i < 2; ++i) { int R, C; stage_rc(tid * 16 + i * 8192, R, C); const int Rb = Epi::PERM ? ((R & ~31) + perm32(R & 31)) : R;
;         voffA[i] = (unsigned)(R * K + C) * 2u; voffB[i] = (unsigned)(Rb * K + C) * 2u; }
;     const size_t kstep = (size_t)(BK * 2);
;     const size_t hstep = (size_t)HALF * K * 2;
;     const size_t tstep = 2 * hstep;
;     const unsigned ldsw = (unsigned)wid * 1024u;
;     const int aoff = lds_byte(wr * 64 + fr, fq * 8), boff = lds_byte(wc * 32 + fr, fq * 8);
;     ...
;         PG8_STAGE(PG8_SB(0, 0), cB, voffB); PG8_STAGE(PG8_SB(0, 1), cB + hstep, voffB); PG8_STAGE(PG8_SA(0, 0), cA, voffA); PG8_STAGE(PG8_SA(0, 1), cA + hstep, voffA);
;         if (wr == 1) PG8_BAR;
;         PG8_WAIT_V(2); PG8_BAR;
;         PG8_STAGE(PG8_SB(1, 0), cB + kstep, voffB); PG8_STAGE(PG8_SA(1, 0), cA + kstep, voffA); PG8_STAGE(PG8_SB(1, 1), cB + hstep + kstep, voffB);
;         PG8_WAIT_V(6); PG8_BAR;
.LBB0_699:
	s_add_u32 s10, s34, 0x7e00000
	s_addc_u32 s11, s35, 0
	s_add_u32 s12, s34, 0x24000000
	s_addc_u32 s13, s35, 0
	s_lshl_b32 s5, s14, 5
	s_mov_b64 s[14:15], 0x80
	s_and_b32 s20, s5, 0x60
	s_add_i32 m0, s46, 0x18000
	v_lshl_add_u64 v[6:7], v[6:7], 0, s[14:15]
	s_lshl_b32 s17, s16, 13
	s_lshl_b32 s21, s20, 7
	s_waitcnt vmcnt(2)
	s_barrier
	global_load_lds_dwordx4 v[6:7], off
	v_lshl_add_u64 v[4:5], v[4:5], 0, s[14:15]
	s_add_i32 m0, s46, 0x1a000
	s_add_i32 s51, s46, 0x8000
	s_add_i32 s52, s46, 0xa000
	global_load_lds_dwordx4 v[4:5], off
	v_lshl_add_u64 v[0:1], v[0:1], 0, s[14:15]
	s_mov_b32 m0, s51
	s_add_u32 s18, s36, 0x80080
	global_load_lds_dwordx4 v[0:1], off
	v_lshl_add_u64 v[0:1], v[2:3], 0, s[14:15]
	s_mov_b32 m0, s52
	s_addc_u32 s19, s37, 0
	global_load_lds_dwordx4 v[0:1], off
	s_add_i32 m0, s46, 0x1c000
	v_lshl_add_u64 v[0:1], s[18:19], 0, v[132:133]
	global_load_lds_dwordx4 v[0:1], off
	v_lshl_add_u64 v[0:1], s[18:19], 0, v[128:129]
	s_add_i32 m0, s46, 0x1e000
	s_sext_i32_i16 s5, s0
	global_load_lds_dwordx4 v[0:1], off
	v_and_b32_e32 v0, 15, v220
	v_lshlrev_b32_e32 v1, 1, v11
	v_lshlrev_b32_e32 v2, 2, v220
	v_lshlrev_b32_e32 v3, 6, v220
	s_movk_i32 s0, 0x3c0
	v_lshl_or_b32 v148, s16, 6, v0
	v_lshl_or_b32 v0, v0, 6, v1
	v_and_b32_e32 v2, 32, v2
	v_and_or_b32 v1, v3, s0, v1
	v_bitop3_b32 v149, s21, v1, v2 bitop3:0xf6
	v_lshlrev_b32_e32 v1, 9, v220
	v_bitop3_b32 v0, v0, s17, v2 bitop3:0xde
	v_and_b32_e32 v1, 0x70000, v1
	v_lshlrev_b32_e32 v2, 12, v12
	v_or3_b32 v1, v9, v1, v2
	v_add_u32_e32 v136, v1, v10
	v_lshlrev_b32_e32 v1, 5, v8
	s_waitcnt vmcnt(6)
	s_cmpk_lt_u32 s1, 0x100
	v_and_b32_e32 v1, 0xf0000, v1
	s_cselect_b64 s[16:17], -1, 0
	v_or3_b32 v1, v9, v1, v2
	s_add_i32 s54, 0, 0x10000
	s_add_i32 s55, 0, 0x14000
	s_ashr_i32 s53, s33, 31
	v_or_b32_e32 v150, s20, v11
	v_mov_b32_e32 v137, v133
	v_add_u32_e32 v138, v1, v10
	v_mov_b32_e32 v139, v133
	v_mov_b64_e32 v[140:141], 0x1600
	v_mov_b64_e32 v[142:143], 0x15ff
	v_add_u32_e32 v151, s54, v149
	v_add_u32_e32 v152, s55, v149
	v_add_u32_e32 v153, 0, v0
	v_mov_b32_e32 v154, 0x358637bd
	s_mov_b32 s56, 0x800000
	s_movk_i32 s57, 0x2c00
	s_barrier
	v_readfirstlane_b32 s101, v220
	s_nop 3
	s_lshr_b32 s101, s101, 6
	s_cmp_lt_u32 s101, 4
	s_cbranch_scc0 .Lprio_skip_2
	s_setprio 1

; #define PG8_STAGE(bufoff, gbase, voff) do { _Pragma("unroll") for (int _i = 0; _i < 2; ++_i) \
;         __builtin_amdgcn_global_load_lds((const unsigned*)((const char*)(gbase) + (voff)[_i]), (PG8_LAS unsigned*)(lds + (bufoff) + ldsw + _i * 8192), 16, 0, 0); } while (0)
; #define PG8_LDA(dst, b, h) do { _Pragma("unroll") for (int m = 0; m < 4; ++m) _Pragma("unroll") for (int k = 0; k < 2; ++k) dst[m][k] = *(const PG8_LAS bf16x8*)(lds + PG8_SA(b, h) + aoff + m * 2048 + k * 1024); } while (0)
; #define PG8_LDB(dst, b, h) do { _Pragma("unroll") for (int n = 0; n < 2; ++n) _Pragma("unroll") for (int k = 0; k < 2; ++k) dst[n][k] = *(const PG8_LAS bf16x8*)(lds + PG8_SB(b, h) + boff + n * 2048 + k * 1024); } while (0)
; #define PG8_MMA(ai, bj, At, Bt) do { __builtin_amdgcn_s_setprio(1); _Pragma("unroll") for (int m = 0; m < 4; ++m) _Pragma("unroll") for (int n = 0; n < 2; ++n) _Pragma("unroll") for (int k = 0; k < 2; ++k) \
;         acc[ai][bj][m][n] = __builtin_amdgcn_mfma_f32_16x16x32_bf16(Bt[n][k], At[m][k], acc[ai][bj][m][n], 0, 0, 0); __builtin_amdgcn_s_setprio(0); } while (0)
; #define PG8_WAIT_V(n) asm volatile("s_waitcnt vmcnt(" #n ")" ::: "memory")
; #define PG8_WAIT_L(n) asm volatile("s_waitcnt lgkmcnt(" #n ")" ::: "memory")
; #define PG8_BAR __builtin_amdgcn_s_barrier()
; #define PG8_SCHED __builtin_amdgcn_sched_barrier(0)
; template <class Epi, class Sched, bool ALIGN_EPI = false, bool SP2 = false>
; __device__ __forceinline__ void gemm_phase(PG8_LAS unsigned char* lds, const Gemm g, const Sched& S, const Epi& E) {
;     ...
;             PG8_LDB(B0, 0, 0); PG8_LDB(B1, 0, 1); PG8_SCHED; PG8_LDA(At, 0, 0); PG8_STAGE(PG8_SA(1, 1), a1 + hstep, voffA);
;             PG8_WAIT_V(8); PG8_WAIT_L(0); PG8_BAR; PG8_MMA(0, 0, At, B0); PG8_MMA(0, 1, At, B1); PG8_BAR; PG8_SCHED;
;             PG8_LDA(At, 0, 1); PG8_STAGE(PG8_SB(0, 0), b2, voffB); PG8_STAGE(PG8_SB(0, 1), b2 + hstep, voffB); PG8_STAGE(PG8_SA(0, 0), a2, voffA);
;             PG8_WAIT_V(8); PG8_WAIT_L(0); PG8_BAR; PG8_MMA(1, 0, At, B0); PG8_MMA(1, 1, At, B1); PG8_BAR; PG8_SCHED;
.LBB0_705:
	ds_read_b128 v[144:147], v151
	ds_read_b128 v[156:159], v151 offset:1024
	ds_read_b128 v[160:163], v151 offset:2048
	ds_read_b128 v[164:167], v151 offset:3072
	ds_read_b128 v[168:171], v152
	ds_read_b128 v[172:175], v152 offset:1024
	ds_read_b128 v[176:179], v152 offset:2048
	ds_read_b128 v[180:183], v152 offset:3072
	s_add_u32 s36, s30, 0xfff80080
	s_addc_u32 s37, s31, -1
	s_cmp_eq_u32 s62, 28
	s_cselect_b32 s39, s21, s37
	s_cselect_b32 s38, s58, s36
	s_cselect_b32 s37, s19, s61
	s_cselect_b32 s36, s59, s60
	s_add_i32 m0, s46, 0xc000
	ds_read_b128 v[184:187], v153
	ds_read_b128 v[188:191], v153 offset:1024
	ds_read_b128 v[192:195], v153 offset:2048
	ds_read_b128 v[196:199], v153 offset:3072
	ds_read_b128 v[200:203], v153 offset:4096
	ds_read_b128 v[204:207], v153 offset:5120
	ds_read_b128 v[208:211], v153 offset:6144
	ds_read_b128 v[212:215], v153 offset:7168
	global_load_lds_dwordx4 v136, s[30:31]
	s_add_i32 m0, s46, 0xe000
	s_nop 0
	global_load_lds_dwordx4 v138, s[30:31]
	s_waitcnt vmcnt(8)
	s_waitcnt lgkmcnt(0)
	s_barrier
	s_waitcnt lgkmcnt(0)
	v_mfma_f32_16x16x32_bf16 v[116:119], v[144:147], v[184:187], v[116:119]
	v_mfma_f32_16x16x32_bf16 v[112:115], v[160:163], v[184:187], v[112:115]
	v_mfma_f32_16x16x32_bf16 v[100:103], v[144:147], v[192:195], v[100:103]
	v_mfma_f32_16x16x32_bf16 v[96:99], v[160:163], v[192:195], v[96:99]
	v_mfma_f32_16x16x32_bf16 v[84:87], v[144:147], v[200:203], v[84:87]
	v_mfma_f32_16x16x32_bf16 v[80:83], v[160:163], v[200:203], v[80:83]
	v_mfma_f32_16x16x32_bf16 v[72:75], v[144:147], v[208:211], v[72:75]
	v_mfma_f32_16x16x32_bf16 v[64:67], v[160:163], v[208:211], v[64:67]
	v_mfma_f32_16x16x32_bf16 v[116:119], v[156:159], v[188:191], v[116:119]
	v_mfma_f32_16x16x32_bf16 v[112:115], v[164:167], v[188:191], v[112:115]
	v_mfma_f32_16x16x32_bf16 v[100:103], v[156:159], v[196:199], v[100:103]
	v_mfma_f32_16x16x32_bf16 v[96:99], v[164:167], v[196:199], v[96:99]
	v_mfma_f32_16x16x32_bf16 v[84:87], v[156:159], v[204:207], v[84:87]
	v_mfma_f32_16x16x32_bf16 v[80:83], v[164:167], v[204:207], v[80:83]
	v_mfma_f32_16x16x32_bf16 v[72:75], v[156:159], v[212:215], v[72:75]
	v_mfma_f32_16x16x32_bf16 v[64:67], v[164:167], v[212:215], v[64:67]
	v_mfma_f32_16x16x32_bf16 v[124:127], v[168:171], v[184:187], v[124:127]
	v_mfma_f32_16x16x32_bf16 v[120:123], v[176:179], v[184:187], v[120:123]
	v_mfma_f32_16x16x32_bf16 v[108:111], v[168:171], v[192:195], v[108:111]
	v_mfma_f32_16x16x32_bf16 v[104:107], v[176:179], v[192:195], v[104:107]
	v_mfma_f32_16x16x32_bf16 v[92:95], v[168:171], v[200:203], v[92:95]
	v_mfma_f32_16x16x32_bf16 v[88:91], v[176:179], v[200:203], v[88:91]
	v_mfma_f32_16x16x32_bf16 v[76:79], v[168:171], v[208:211], v[76:79]
	v_mfma_f32_16x16x32_bf16 v[68:71], v[176:179], v[208:211], v[68:71]
	v_mfma_f32_16x16x32_bf16 v[124:127], v[172:175], v[188:191], v[124:127]
	v_mfma_f32_16x16x32_bf16 v[120:123], v[180:183], v[188:191], v[120:123]
	v_mfma_f32_16x16x32_bf16 v[108:111], v[172:175], v[196:199], v[108:111]
	v_mfma_f32_16x16x32_bf16 v[104:107], v[180:183], v[196:199], v[104:107]
	v_mfma_f32_16x16x32_bf16 v[92:95], v[172:175], v[204:207], v[92:95]
	v_mfma_f32_16x16x32_bf16 v[88:91], v[180:183], v[204:207], v[88:91]
	v_mfma_f32_16x16x32_bf16 v[76:79], v[172:175], v[212:215], v[76:79]
	v_mfma_f32_16x16x32_bf16 v[68:71], v[180:183], v[212:215], v[68:71]
	s_barrier
	s_add_i32 s63, s54, s43
	s_mov_b32 m0, s63
	ds_read_b128 v[184:187], v153 offset:16384
	ds_read_b128 v[188:191], v153 offset:17408
	ds_read_b128 v[192:195], v153 offset:18432
	ds_read_b128 v[196:199], v153 offset:19456
	ds_read_b128 v[200:203], v153 offset:20480
	ds_read_b128 v[204:207], v153 offset:21504
	ds_read_b128 v[208:211], v153 offset:22528
	ds_read_b128 v[212:215], v153 offset:23552
	global_load_lds_dwordx4 v132, s[36:37]
	s_add_i32 m0, s63, 0x2000
	s_add_u32 s64, s36, 0x80000
	s_addc_u32 s65, s37, 0
	s_add_i32 s63, s55, s43
	global_load_lds_dwordx4 v128, s[36:37]
	s_mov_b32 m0, s63
	s_nop 0
	global_load_lds_dwordx4 v132, s[64:65]
	s_add_i32 m0, s63, 0x2000
	s_nop 0
	global_load_lds_dwordx4 v128, s[64:65]
	s_mov_b32 m0, s46
	s_nop 0
	global_load_lds_dwordx4 v134, s[38:39]
	s_mov_b32 m0, s47
	s_nop 0
	global_load_lds_dwordx4 v130, s[38:39]
	s_waitcnt vmcnt(8)
	s_waitcnt lgkmcnt(0)
	s_barrier
	s_waitcnt lgkmcnt(0)
	v_mfma_f32_16x16x32_bf16 v[56:59], v[144:147], v[184:187], v[56:59]
	v_mfma_f32_16x16x32_bf16 v[48:51], v[160:163], v[184:187], v[48:51]
	v_mfma_f32_16x16x32_bf16 v[40:43], v[144:147], v[192:195], v[40:43]
	v_mfma_f32_16x16x32_bf16 v[32:35], v[160:163], v[192:195], v[32:35]
	v_mfma_f32_16x16x32_bf16 v[24:27], v[144:147], v[200:203], v[24:27]
	v_mfma_f32_16x16x32_bf16 v[16:19], v[160:163], v[200:203], v[16:19]
	v_mfma_f32_16x16x32_bf16 v[8:11], v[144:147], v[208:211], v[8:11]
	v_mfma_f32_16x16x32_bf16 v[0:3], v[160:163], v[208:211], v[0:3]
	v_mfma_f32_16x16x32_bf16 v[56:59], v[156:159], v[188:191], v[56:59]
	v_mfma_f32_16x16x32_bf16 v[48:51], v[164:167], v[188:191], v[48:51]
	v_mfma_f32_16x16x32_bf16 v[40:43], v[156:159], v[196:199], v[40:43]
	v_mfma_f32_16x16x32_bf16 v[32:35], v[164:167], v[196:199], v[32:35]
	v_mfma_f32_16x16x32_bf16 v[24:27], v[156:159], v[204:207], v[24:27]
	v_mfma_f32_16x16x32_bf16 v[16:19], v[164:167], v[204:207], v[16:19]
	v_mfma_f32_16x16x32_bf16 v[8:11], v[156:159], v[212:215], v[8:11]
	v_mfma_f32_16x16x32_bf16 v[0:3], v[164:167], v[212:215], v[0:3]
	v_mfma_f32_16x16x32_bf16 v[60:63], v[168:171], v[184:187], v[60:63]
	v_mfma_f32_16x16x32_bf16 v[52:55], v[176:179], v[184:187], v[52:55]
	v_mfma_f32_16x16x32_bf16 v[44:47], v[168:171], v[192:195], v[44:47]
	v_mfma_f32_16x16x32_bf16 v[36:39], v[176:179], v[192:195], v[36:39]
	v_mfma_f32_16x16x32_bf16 v[28:31], v[168:171], v[200:203], v[28:31]
	v_mfma_f32_16x16x32_bf16 v[20:23], v[176:179], v[200:203], v[20:23]
	v_mfma_f32_16x16x32_bf16 v[12:15], v[168:171], v[208:211], v[12:15]
	v_mfma_f32_16x16x32_bf16 v[4:7], v[176:179], v[208:211], v[4:7]
	v_mfma_f32_16x16x32_bf16 v[60:63], v[172:175], v[188:191], v[60:63]
	v_mfma_f32_16x16x32_bf16 v[52:55], v[180:183], v[188:191], v[52:55]
	v_mfma_f32_16x16x32_bf16 v[44:47], v[172:175], v[196:199], v[44:47]
	v_mfma_f32_16x16x32_bf16 v[36:39], v[180:183], v[196:199], v[36:39]
	v_mfma_f32_16x16x32_bf16 v[28:31], v[172:175], v[204:207], v[28:31]
	v_mfma_f32_16x16x32_bf16 v[20:23], v[180:183], v[204:207], v[20:23]
	v_mfma_f32_16x16x32_bf16 v[12:15], v[172:175], v[212:215], v[12:15]
	v_mfma_f32_16x16x32_bf16 v[4:7], v[180:183], v[212:215], v[4:7]
	s_barrier
; #define PG8_STAGE(bufoff, gbase, voff) do { _Pragma("unroll") for (int _i = 0; _i < 2; ++_i) \
;         __builtin_amdgcn_global_load_lds((const unsigned*)((const char*)(gbase) + (voff)[_i]), (PG8_LAS unsigned*)(lds + (bufoff) + ldsw + _i * 8192), 16, 0, 0); } while (0)
; #define PG8_LDA(dst, b, h) do { _Pragma("unroll") for (int m = 0; m < 4; ++m) _Pragma("unroll") for (int k = 0; k < 2; ++k) dst[m][k] = *(const PG8_LAS bf16x8*)(lds + PG8_SA(b, h) + aoff + m * 2048 + k * 1024); } while (0)
; #define PG8_LDB(dst, b, h) do { _Pragma("unroll") for (int n = 0; n < 2; ++n) _Pragma("unroll") for (int k = 0; k < 2; ++k) dst[n][k] = *(const PG8_LAS bf16x8*)(lds + PG8_SB(b, h) + boff + n * 2048 + k * 1024); } while (0)
; #define PG8_MMA(ai, bj, At, Bt) do { __builtin_amdgcn_s_setprio(1); _Pragma("unroll") for (int m = 0; m < 4; ++m) _Pragma("unroll") for (int n = 0; n < 2; ++n) _Pragma("unroll") for (int k = 0; k < 2; ++k) \
;         acc[ai][bj][m][n] = __builtin_amdgcn_mfma_f32_16x16x32_bf16(Bt[n][k], At[m][k], acc[ai][bj][m][n], 0, 0, 0); __builtin_amdgcn_s_setprio(0); } while (0)
; #define PG8_WAIT_V(n) asm volatile("s_waitcnt vmcnt(" #n ")" ::: "memory")
; #define PG8_WAIT_L(n) asm volatile("s_waitcnt lgkmcnt(" #n ")" ::: "memory")
; #define PG8_BAR __builtin_amdgcn_s_barrier()
; #define PG8_SCHED __builtin_amdgcn_sched_barrier(0)
; template <class Epi, class Sched, bool ALIGN_EPI = false, bool SP2 = false>
; __device__ __forceinline__ void gemm_phase(PG8_LAS unsigned char* lds, const Gemm g, const Sched& S, const Epi& E) {
;     ...
;             PG8_LDB(B0, 1, 0); PG8_LDB(B1, 1, 1); PG8_SCHED; PG8_LDA(At, 1, 0); PG8_STAGE(PG8_SA(0, 1), a2 + hstep, voffA);
;             PG8_WAIT_V(8); PG8_WAIT_L(0); PG8_BAR; PG8_MMA(0, 0, At, B0); PG8_MMA(0, 1, At, B1); PG8_BAR; PG8_SCHED;
;             PG8_LDA(At, 1, 1); PG8_STAGE(PG8_SB(1, 0), b3, voffB); PG8_STAGE(PG8_SB(1, 1), b3 + hstep, voffB); PG8_STAGE(PG8_SA(1, 0), a3, voffA);
;             PG8_WAIT_V(8); PG8_WAIT_L(0); PG8_BAR; PG8_MMA(1, 0, At, B0); PG8_MMA(1, 1, At, B1); PG8_BAR; PG8_SCHED;
	s_add_i32 s63, 0, 0x18000
	v_add_u32_e32 v155, s63, v149
	s_add_i32 s64, 0, 0x1c000
	ds_read_b128 v[144:147], v155
	ds_read_b128 v[156:159], v155 offset:1024
	ds_read_b128 v[160:163], v155 offset:2048
	ds_read_b128 v[164:167], v155 offset:3072
	v_add_u32_e32 v155, s64, v149
	ds_read_b128 v[168:171], v155
	ds_read_b128 v[172:175], v155 offset:1024
	ds_read_b128 v[176:179], v155 offset:2048
	ds_read_b128 v[180:183], v155 offset:3072
	s_add_u32 s38, s38, 0x80000
	s_addc_u32 s39, s39, 0
	s_mov_b32 m0, s48
	ds_read_b128 v[184:187], v153 offset:32768
	ds_read_b128 v[188:191], v153 offset:33792
	ds_read_b128 v[192:195], v153 offset:34816
	ds_read_b128 v[196:199], v153 offset:35840
	ds_read_b128 v[200:203], v153 offset:36864
	ds_read_b128 v[204:207], v153 offset:37888
	ds_read_b128 v[208:211], v153 offset:38912
	ds_read_b128 v[212:215], v153 offset:39936
	global_load_lds_dwordx4 v134, s[38:39]
	s_mov_b32 m0, s49
	s_nop 0
	global_load_lds_dwordx4 v130, s[38:39]
	s_waitcnt vmcnt(8)
	s_waitcnt lgkmcnt(0)
	s_barrier
	s_waitcnt lgkmcnt(0)
	v_mfma_f32_16x16x32_bf16 v[116:119], v[144:147], v[184:187], v[116:119]
	v_mfma_f32_16x16x32_bf16 v[112:115], v[160:163], v[184:187], v[112:115]
	v_mfma_f32_16x16x32_bf16 v[100:103], v[144:147], v[192:195], v[100:103]
	v_mfma_f32_16x16x32_bf16 v[96:99], v[160:163], v[192:195], v[96:99]
	v_mfma_f32_16x16x32_bf16 v[84:87], v[144:147], v[200:203], v[84:87]
	v_mfma_f32_16x16x32_bf16 v[80:83], v[160:163], v[200:203], v[80:83]
	v_mfma_f32_16x16x32_bf16 v[72:75], v[144:147], v[208:211], v[72:75]
	v_mfma_f32_16x16x32_bf16 v[64:67], v[160:163], v[208:211], v[64:67]
	v_mfma_f32_16x16x32_bf16 v[116:119], v[156:159], v[188:191], v[116:119]
	v_mfma_f32_16x16x32_bf16 v[112:115], v[164:167], v[188:191], v[112:115]
	v_mfma_f32_16x16x32_bf16 v[100:103], v[156:159], v[196:199], v[100:103]
	v_mfma_f32_16x16x32_bf16 v[96:99], v[164:167], v[196:199], v[96:99]
	v_mfma_f32_16x16x32_bf16 v[84:87], v[156:159], v[204:207], v[84:87]
	v_mfma_f32_16x16x32_bf16 v[80:83], v[164:167], v[204:207], v[80:83]
	v_mfma_f32_16x16x32_bf16 v[72:75], v[156:159], v[212:215], v[72:75]
	v_mfma_f32_16x16x32_bf16 v[64:67], v[164:167], v[212:215], v[64:67]
	v_mfma_f32_16x16x32_bf16 v[124:127], v[168:171], v[184:187], v[124:127]
	v_mfma_f32_16x16x32_bf16 v[120:123], v[176:179], v[184:187], v[120:123]
	v_mfma_f32_16x16x32_bf16 v[108:111], v[168:171], v[192:195], v[108:111]
	v_mfma_f32_16x16x32_bf16 v[104:107], v[176:179], v[192:195], v[104:107]
	v_mfma_f32_16x16x32_bf16 v[92:95], v[168:171], v[200:203], v[92:95]
	v_mfma_f32_16x16x32_bf16 v[88:91], v[176:179], v[200:203], v[88:91]
	v_mfma_f32_16x16x32_bf16 v[76:79], v[168:171], v[208:211], v[76:79]
	v_mfma_f32_16x16x32_bf16 v[68:71], v[176:179], v[208:211], v[68:71]
	v_mfma_f32_16x16x32_bf16 v[124:127], v[172:175], v[188:191], v[124:127]
	v_mfma_f32_16x16x32_bf16 v[120:123], v[180:183], v[188:191], v[120:123]
	v_mfma_f32_16x16x32_bf16 v[108:111], v[172:175], v[196:199], v[108:111]
	v_mfma_f32_16x16x32_bf16 v[104:107], v[180:183], v[196:199], v[104:107]
	v_mfma_f32_16x16x32_bf16 v[92:95], v[172:175], v[204:207], v[92:95]
	v_mfma_f32_16x16x32_bf16 v[88:91], v[180:183], v[204:207], v[88:91]
	v_mfma_f32_16x16x32_bf16 v[76:79], v[172:175], v[212:215], v[76:79]
	v_mfma_f32_16x16x32_bf16 v[68:71], v[180:183], v[212:215], v[68:71]
	s_barrier
	s_mov_b64 s[66:67], s[38:39]
	s_add_i32 s38, s63, s43
	s_mov_b32 m0, s38
	ds_read_b128 v[184:187], v153 offset:49152
	ds_read_b128 v[188:191], v153 offset:50176
	ds_read_b128 v[192:195], v153 offset:51200
	ds_read_b128 v[196:199], v153 offset:52224
	ds_read_b128 v[200:203], v153 offset:53248
	ds_read_b128 v[204:207], v153 offset:54272
	ds_read_b128 v[208:211], v153 offset:55296
	ds_read_b128 v[212:215], v153 offset:56320
	s_add_u32 s68, s36, 0x80
	s_addc_u32 s69, s37, 0
	global_load_lds_dwordx4 v132, s[68:69]
	s_add_i32 m0, s38, 0x2000
	s_add_u32 s36, s36, 0x80080
	s_addc_u32 s37, s37, 0
	s_add_i32 s38, s64, s43
	global_load_lds_dwordx4 v128, s[68:69]
	s_mov_b32 m0, s38
	s_nop 0
	global_load_lds_dwordx4 v132, s[36:37]
	s_add_i32 m0, s38, 0x2000
	s_nop 0
	global_load_lds_dwordx4 v128, s[36:37]
	s_mov_b32 m0, s51
	s_nop 0
	s_add_u32 s70, s66, 0xfff80080
	s_addc_u32 s71, s67, -1
	global_load_lds_dwordx4 v134, s[70:71]
	s_mov_b32 m0, s52
	s_nop 0
	global_load_lds_dwordx4 v130, s[70:71]
	s_waitcnt vmcnt(8)
	s_waitcnt lgkmcnt(0)
	s_barrier
	s_waitcnt lgkmcnt(0)
	v_mfma_f32_16x16x32_bf16 v[56:59], v[144:147], v[184:187], v[56:59]
	v_mfma_f32_16x16x32_bf16 v[48:51], v[160:163], v[184:187], v[48:51]
	v_mfma_f32_16x16x32_bf16 v[40:43], v[144:147], v[192:195], v[40:43]
	v_mfma_f32_16x16x32_bf16 v[32:35], v[160:163], v[192:195], v[32:35]
	v_mfma_f32_16x16x32_bf16 v[24:27], v[144:147], v[200:203], v[24:27]
	v_mfma_f32_16x16x32_bf16 v[16:19], v[160:163], v[200:203], v[16:19]
	v_mfma_f32_16x16x32_bf16 v[8:11], v[144:147], v[208:211], v[8:11]
	v_mfma_f32_16x16x32_bf16 v[0:3], v[160:163], v[208:211], v[0:3]
	v_mfma_f32_16x16x32_bf16 v[56:59], v[156:159], v[188:191], v[56:59]
	v_mfma_f32_16x16x32_bf16 v[48:51], v[164:167], v[188:191], v[48:51]
	v_mfma_f32_16x16x32_bf16 v[40:43], v[156:159], v[196:199], v[40:43]
	v_mfma_f32_16x16x32_bf16 v[32:35], v[164:167], v[196:199], v[32:35]
	v_mfma_f32_16x16x32_bf16 v[24:27], v[156:159], v[204:207], v[24:27]
	v_mfma_f32_16x16x32_bf16 v[16:19], v[164:167], v[204:207], v[16:19]
	v_mfma_f32_16x16x32_bf16 v[8:11], v[156:159], v[212:215], v[8:11]
	v_mfma_f32_16x16x32_bf16 v[0:3], v[164:167], v[212:215], v[0:3]
	v_mfma_f32_16x16x32_bf16 v[60:63], v[168:171], v[184:187], v[60:63]
	v_mfma_f32_16x16x32_bf16 v[52:55], v[176:179], v[184:187], v[52:55]
	v_mfma_f32_16x16x32_bf16 v[44:47], v[168:171], v[192:195], v[44:47]
	v_mfma_f32_16x16x32_bf16 v[36:39], v[176:179], v[192:195], v[36:39]
	v_mfma_f32_16x16x32_bf16 v[28:31], v[168:171], v[200:203], v[28:31]
	v_mfma_f32_16x16x32_bf16 v[20:23], v[176:179], v[200:203], v[20:23]
	v_mfma_f32_16x16x32_bf16 v[12:15], v[168:171], v[208:211], v[12:15]
	v_mfma_f32_16x16x32_bf16 v[4:7], v[176:179], v[208:211], v[4:7]
	v_mfma_f32_16x16x32_bf16 v[60:63], v[172:175], v[188:191], v[60:63]
	v_mfma_f32_16x16x32_bf16 v[52:55], v[180:183], v[188:191], v[52:55]
	v_mfma_f32_16x16x32_bf16 v[44:47], v[172:175], v[196:199], v[44:47]
	v_mfma_f32_16x16x32_bf16 v[36:39], v[180:183], v[196:199], v[36:39]
	v_mfma_f32_16x16x32_bf16 v[28:31], v[172:175], v[204:207], v[28:31]
	v_mfma_f32_16x16x32_bf16 v[20:23], v[180:183], v[204:207], v[20:23]
	v_mfma_f32_16x16x32_bf16 v[12:15], v[172:175], v[212:215], v[12:15]
	v_mfma_f32_16x16x32_bf16 v[4:7], v[180:183], v[212:215], v[4:7]
	s_barrier
	s_add_i32 s62, s62, 2
	s_add_u32 s30, s30, 0x100
	s_addc_u32 s31, s31, 0
	s_add_u32 s60, s60, 0x100
	s_addc_u32 s61, s61, 0
	s_cmp_gt_u32 s62, 29
	s_cbranch_scc0 .LBB0_705
	s_and_b64 vcc, exec, s[16:17]
	s_cbranch_vccz .LBB0_708
	s_barrier

; #define PG8_STAGE(bufoff, gbase, voff) do { _Pragma("unroll") for (int _i = 0; _i < 2; ++_i) \
;         __builtin_amdgcn_global_load_lds((const unsigned*)((const char*)(gbase) + (voff)[_i]), (PG8_LAS unsigned*)(lds + (bufoff) + ldsw + _i * 8192), 16, 0, 0); } while (0)
; #define PG8_WAIT_V(n) asm volatile("s_waitcnt vmcnt(" #n ")" ::: "memory")
; #define PG8_BAR __builtin_amdgcn_s_barrier()
; template <class Epi, class Sched, bool ALIGN_EPI = false, bool SP2 = false>
; __device__ __forceinline__ void gemm_phase(PG8_LAS unsigned char* lds, const Gemm g, const Sched& S, const Epi& E) {
;     ...
;     for (int i = 0; i < 2; ++i) { int R, C; stage_rc(tid * 16 + i * 8192, R, C); const int Rb = Epi::PERM ? ((R & ~31) + perm32(R & 31)) : R;
;         voffA[i] = (unsigned)(R * K + C) * 2u; voffB[i] = (unsigned)(Rb * K + C) * 2u; }
;     const size_t kstep = (size_t)(BK * 2);
;     const size_t hstep = (size_t)HALF * K * 2;
;     const size_t tstep = 2 * hstep;
;     const unsigned ldsw = (unsigned)wid * 1024u;
;     const int aoff = lds_byte(wr * 64 + fr, fq * 8), boff = lds_byte(wc * 32 + fr, fq * 8);
;     ...
;         PG8_STAGE(PG8_SB(0, 0), cB, voffB); PG8_STAGE(PG8_SB(0, 1), cB + hstep, voffB); PG8_STAGE(PG8_SA(0, 0), cA, voffA); PG8_STAGE(PG8_SA(0, 1), cA + hstep, voffA);
;         if (wr == 1) PG8_BAR;
;         PG8_WAIT_V(2); PG8_BAR;
;         PG8_STAGE(PG8_SB(1, 0), cB + kstep, voffB); PG8_STAGE(PG8_SA(1, 0), cA + kstep, voffA); PG8_STAGE(PG8_SB(1, 1), cB + hstep + kstep, voffB);
;         PG8_WAIT_V(6); PG8_BAR;
.LBB0_728:
	s_lshl_b32 s5, s5, 5
	s_mov_b64 s[10:11], 0x80
	s_and_b32 s5, s5, 0x60
	s_add_i32 m0, s37, 0x18000
	v_lshl_add_u64 v[6:7], v[6:7], 0, s[10:11]
	s_lshl_b32 s14, s0, 13
	s_lshl_b32 s15, s5, 7
	s_waitcnt vmcnt(2)
	s_barrier
	global_load_lds_dwordx4 v[6:7], off
	v_lshl_add_u64 v[2:3], v[2:3], 0, s[10:11]
	s_add_i32 m0, s37, 0x1a000
	s_add_i32 s42, s37, 0x8000
	s_add_i32 s43, s37, 0xa000
	global_load_lds_dwordx4 v[2:3], off
	v_lshl_add_u64 v[0:1], v[0:1], 0, s[10:11]
	s_mov_b32 m0, s42
	s_add_u32 s12, s24, 0x160080
	global_load_lds_dwordx4 v[0:1], off
	v_lshl_add_u64 v[0:1], v[4:5], 0, s[10:11]
	s_mov_b32 m0, s43
	s_addc_u32 s13, s25, 0
	global_load_lds_dwordx4 v[0:1], off
	s_add_i32 m0, s37, 0x1c000
	v_lshl_add_u64 v[0:1], s[12:13], 0, v[130:131]
	global_load_lds_dwordx4 v[0:1], off
	v_lshl_add_u64 v[0:1], s[12:13], 0, v[134:135]
	s_add_i32 m0, s37, 0x1e000
	v_lshlrev_b32_e32 v2, 2, v220
	global_load_lds_dwordx4 v[0:1], off
	v_and_b32_e32 v0, 15, v220
	v_lshl_or_b32 v150, s0, 6, v0
	v_lshlrev_b32_e32 v1, 1, v10
	v_lshlrev_b32_e32 v3, 6, v220
	s_movk_i32 s0, 0x3c0
	v_lshl_or_b32 v0, v0, 6, v1
	v_and_b32_e32 v2, 32, v2
	v_and_or_b32 v1, v3, s0, v1
	v_bitop3_b32 v151, s15, v1, v2 bitop3:0xf6
	s_waitcnt vmcnt(6)
	s_cmpk_lt_u32 s4, 0x100
	v_add_u16_e32 v1, v8, v9
	v_bitop3_b32 v0, v0, s14, v2 bitop3:0xde
	s_cselect_b64 s[12:13], -1, 0
	v_lshrrev_b16_e32 v1, 1, v1
	s_add_i32 s45, 0, 0x10000
	s_add_i32 s46, 0, 0x14000
	s_sext_i32_i8 s54, s1
	s_ashr_i32 s44, s33, 31
	v_or_b32_e32 v152, s5, v10
	v_add_lshl_u32 v136, v11, v1, 1
	v_mov_b32_e32 v137, v131
	v_add_lshl_u32 v138, v12, v1, 1
	v_mov_b32_e32 v139, v131
	v_mov_b64_e32 v[140:141], 0x400
	v_mov_b64_e32 v[142:143], 0x3ff
	v_add_u32_e32 v153, s45, v151
	v_add_u32_e32 v154, s46, v151
	v_add_u32_e32 v155, 0, v0
	s_mov_b64 s[14:15], 0x100000
	s_mov_b32 s47, 0x100000
	s_mov_b64 s[16:17], 0x120000
	s_mov_b32 s48, 0x120000
	s_mov_b64 s[18:19], 0x140000
	s_mov_b32 s49, 0x140000
	s_mov_b32 s50, 0x160000
	s_barrier
	v_readfirstlane_b32 s101, v220
	s_nop 3
	s_lshr_b32 s101, s101, 6
	s_cmp_lt_u32 s101, 4
	s_cbranch_scc0 .Lprio_skip_3
	s_setprio 1

; #define PG8_STAGE(bufoff, gbase, voff) do { _Pragma("unroll") for (int _i = 0; _i < 2; ++_i) \
;         __builtin_amdgcn_global_load_lds((const unsigned*)((const char*)(gbase) + (voff)[_i]), (PG8_LAS unsigned*)(lds + (bufoff) + ldsw + _i * 8192), 16, 0, 0); } while (0)
; #define PG8_LDA(dst, b, h) do { _Pragma("unroll") for (int m = 0; m < 4; ++m) _Pragma("unroll") for (int k = 0; k < 2; ++k) dst[m][k] = *(const PG8_LAS bf16x8*)(lds + PG8_SA(b, h) + aoff + m * 2048 + k * 1024); } while (0)
; #define PG8_LDB(dst, b, h) do { _Pragma("unroll") for (int n = 0; n < 2; ++n) _Pragma("unroll") for (int k = 0; k < 2; ++k) dst[n][k] = *(const PG8_LAS bf16x8*)(lds + PG8_SB(b, h) + boff + n * 2048 + k * 1024); } while (0)
; #define PG8_MMA(ai, bj, At, Bt) do { __builtin_amdgcn_s_setprio(1); _Pragma("unroll") for (int m = 0; m < 4; ++m) _Pragma("unroll") for (int n = 0; n < 2; ++n) _Pragma("unroll") for (int k = 0; k < 2; ++k) \
;         acc[ai][bj][m][n] = __builtin_amdgcn_mfma_f32_16x16x32_bf16(Bt[n][k], At[m][k], acc[ai][bj][m][n], 0, 0, 0); __builtin_amdgcn_s_setprio(0); } while (0)
; #define PG8_WAIT_V(n) asm volatile("s_waitcnt vmcnt(" #n ")" ::: "memory")
; #define PG8_WAIT_L(n) asm volatile("s_waitcnt lgkmcnt(" #n ")" ::: "memory")
; #define PG8_BAR __builtin_amdgcn_s_barrier()
; #define PG8_SCHED __builtin_amdgcn_sched_barrier(0)
; template <class Epi, class Sched, bool ALIGN_EPI = false, bool SP2 = false>
; __device__ __forceinline__ void gemm_phase(PG8_LAS unsigned char* lds, const Gemm g, const Sched& S, const Epi& E) {
;     ...
;             PG8_LDB(B0, 0, 0); PG8_LDB(B1, 0, 1); PG8_SCHED; PG8_LDA(At, 0, 0); PG8_STAGE(PG8_SA(1, 1), a1 + hstep, voffA);
;             PG8_WAIT_V(8); PG8_WAIT_L(0); PG8_BAR; PG8_MMA(0, 0, At, B0); PG8_MMA(0, 1, At, B1); PG8_BAR; PG8_SCHED;
;             PG8_LDA(At, 0, 1); PG8_STAGE(PG8_SB(0, 0), b2, voffB); PG8_STAGE(PG8_SB(0, 1), b2 + hstep, voffB); PG8_STAGE(PG8_SA(0, 0), a2, voffA);
;             PG8_WAIT_V(8); PG8_WAIT_L(0); PG8_BAR; PG8_MMA(1, 0, At, B0); PG8_MMA(1, 1, At, B1); PG8_BAR; PG8_SCHED;
.LBB0_742:
	ds_read_b128 v[144:147], v153
	ds_read_b128 v[156:159], v153 offset:1024
	ds_read_b128 v[160:163], v153 offset:2048
	ds_read_b128 v[164:167], v153 offset:3072
	ds_read_b128 v[168:171], v154
	ds_read_b128 v[172:175], v154 offset:1024
	ds_read_b128 v[176:179], v154 offset:2048
	ds_read_b128 v[180:183], v154 offset:3072
	s_add_u32 s24, s22, 0xffea0080
	s_addc_u32 s25, s23, -1
	s_cmpk_eq_i32 s57, 0x54
	s_cselect_b32 s29, s5, s25
	s_cselect_b32 s28, s4, s24
	s_cselect_b32 s25, s21, s56
	s_cselect_b32 s24, s20, s55
	s_add_i32 m0, s37, 0xc000
	ds_read_b128 v[184:187], v155
	ds_read_b128 v[188:191], v155 offset:1024
	ds_read_b128 v[192:195], v155 offset:2048
	ds_read_b128 v[196:199], v155 offset:3072
	ds_read_b128 v[200:203], v155 offset:4096
	ds_read_b128 v[204:207], v155 offset:5120
	ds_read_b128 v[208:211], v155 offset:6144
	ds_read_b128 v[212:215], v155 offset:7168
	global_load_lds_dwordx4 v136, s[22:23]
	s_add_i32 m0, s37, 0xe000
	s_nop 0
	global_load_lds_dwordx4 v138, s[22:23]
	s_waitcnt vmcnt(8)
	s_waitcnt lgkmcnt(0)
	s_barrier
	s_waitcnt lgkmcnt(0)
	v_mfma_f32_16x16x32_bf16 v[124:127], v[144:147], v[184:187], v[124:127]
	v_mfma_f32_16x16x32_bf16 v[120:123], v[160:163], v[184:187], v[120:123]
	v_mfma_f32_16x16x32_bf16 v[108:111], v[144:147], v[192:195], v[108:111]
	v_mfma_f32_16x16x32_bf16 v[104:107], v[160:163], v[192:195], v[104:107]
	v_mfma_f32_16x16x32_bf16 v[92:95], v[144:147], v[200:203], v[92:95]
	v_mfma_f32_16x16x32_bf16 v[88:91], v[160:163], v[200:203], v[88:91]
	v_mfma_f32_16x16x32_bf16 v[76:79], v[144:147], v[208:211], v[76:79]
	v_mfma_f32_16x16x32_bf16 v[72:75], v[160:163], v[208:211], v[72:75]
	v_mfma_f32_16x16x32_bf16 v[124:127], v[156:159], v[188:191], v[124:127]
	v_mfma_f32_16x16x32_bf16 v[120:123], v[164:167], v[188:191], v[120:123]
	v_mfma_f32_16x16x32_bf16 v[108:111], v[156:159], v[196:199], v[108:111]
	v_mfma_f32_16x16x32_bf16 v[104:107], v[164:167], v[196:199], v[104:107]
	v_mfma_f32_16x16x32_bf16 v[92:95], v[156:159], v[204:207], v[92:95]
	v_mfma_f32_16x16x32_bf16 v[88:91], v[164:167], v[204:207], v[88:91]
	v_mfma_f32_16x16x32_bf16 v[76:79], v[156:159], v[212:215], v[76:79]
	v_mfma_f32_16x16x32_bf16 v[72:75], v[164:167], v[212:215], v[72:75]
	v_mfma_f32_16x16x32_bf16 v[116:119], v[168:171], v[184:187], v[116:119]
	v_mfma_f32_16x16x32_bf16 v[112:115], v[176:179], v[184:187], v[112:115]
	v_mfma_f32_16x16x32_bf16 v[100:103], v[168:171], v[192:195], v[100:103]
	v_mfma_f32_16x16x32_bf16 v[96:99], v[176:179], v[192:195], v[96:99]
	v_mfma_f32_16x16x32_bf16 v[84:87], v[168:171], v[200:203], v[84:87]
	v_mfma_f32_16x16x32_bf16 v[80:83], v[176:179], v[200:203], v[80:83]
	v_mfma_f32_16x16x32_bf16 v[68:71], v[168:171], v[208:211], v[68:71]
	v_mfma_f32_16x16x32_bf16 v[64:67], v[176:179], v[208:211], v[64:67]
	v_mfma_f32_16x16x32_bf16 v[116:119], v[172:175], v[188:191], v[116:119]
	v_mfma_f32_16x16x32_bf16 v[112:115], v[180:183], v[188:191], v[112:115]
	v_mfma_f32_16x16x32_bf16 v[100:103], v[172:175], v[196:199], v[100:103]
	v_mfma_f32_16x16x32_bf16 v[96:99], v[180:183], v[196:199], v[96:99]
	v_mfma_f32_16x16x32_bf16 v[84:87], v[172:175], v[204:207], v[84:87]
	v_mfma_f32_16x16x32_bf16 v[80:83], v[180:183], v[204:207], v[80:83]
	v_mfma_f32_16x16x32_bf16 v[68:71], v[172:175], v[212:215], v[68:71]
	v_mfma_f32_16x16x32_bf16 v[64:67], v[180:183], v[212:215], v[64:67]
	s_barrier
	s_add_i32 s58, s45, s36
	s_mov_b32 m0, s58
	ds_read_b128 v[184:187], v155 offset:16384
	ds_read_b128 v[188:191], v155 offset:17408
	ds_read_b128 v[192:195], v155 offset:18432
	ds_read_b128 v[196:199], v155 offset:19456
	ds_read_b128 v[200:203], v155 offset:20480
	ds_read_b128 v[204:207], v155 offset:21504
	ds_read_b128 v[208:211], v155 offset:22528
	ds_read_b128 v[212:215], v155 offset:23552
	global_load_lds_dwordx4 v130, s[24:25]
	s_add_i32 m0, s58, 0x2000
	s_add_u32 s58, s24, 0x160000
	s_addc_u32 s59, s25, 0
	s_add_i32 s60, s46, s36
	global_load_lds_dwordx4 v134, s[24:25]
	s_mov_b32 m0, s60
	s_nop 0
	global_load_lds_dwordx4 v130, s[58:59]
	s_add_i32 m0, s60, 0x2000
	s_nop 0
	global_load_lds_dwordx4 v134, s[58:59]
	s_mov_b32 m0, s37
	s_nop 0
	global_load_lds_dwordx4 v128, s[28:29]
	s_mov_b32 m0, s38
	s_nop 0
	global_load_lds_dwordx4 v132, s[28:29]
	s_waitcnt vmcnt(8)
	s_waitcnt lgkmcnt(0)
	s_barrier
	s_waitcnt lgkmcnt(0)
	v_mfma_f32_16x16x32_bf16 v[60:63], v[144:147], v[184:187], v[60:63]
	v_mfma_f32_16x16x32_bf16 v[56:59], v[160:163], v[184:187], v[56:59]
	v_mfma_f32_16x16x32_bf16 v[44:47], v[144:147], v[192:195], v[44:47]
	v_mfma_f32_16x16x32_bf16 v[40:43], v[160:163], v[192:195], v[40:43]
	v_mfma_f32_16x16x32_bf16 v[28:31], v[144:147], v[200:203], v[28:31]
	v_mfma_f32_16x16x32_bf16 v[24:27], v[160:163], v[200:203], v[24:27]
	v_mfma_f32_16x16x32_bf16 v[12:15], v[144:147], v[208:211], v[12:15]
	v_mfma_f32_16x16x32_bf16 v[8:11], v[160:163], v[208:211], v[8:11]
	v_mfma_f32_16x16x32_bf16 v[60:63], v[156:159], v[188:191], v[60:63]
	v_mfma_f32_16x16x32_bf16 v[56:59], v[164:167], v[188:191], v[56:59]
	v_mfma_f32_16x16x32_bf16 v[44:47], v[156:159], v[196:199], v[44:47]
	v_mfma_f32_16x16x32_bf16 v[40:43], v[164:167], v[196:199], v[40:43]
	v_mfma_f32_16x16x32_bf16 v[28:31], v[156:159], v[204:207], v[28:31]
	v_mfma_f32_16x16x32_bf16 v[24:27], v[164:167], v[204:207], v[24:27]
	v_mfma_f32_16x16x32_bf16 v[12:15], v[156:159], v[212:215], v[12:15]
	v_mfma_f32_16x16x32_bf16 v[8:11], v[164:167], v[212:215], v[8:11]
	v_mfma_f32_16x16x32_bf16 v[52:55], v[168:171], v[184:187], v[52:55]
	v_mfma_f32_16x16x32_bf16 v[48:51], v[176:179], v[184:187], v[48:51]
	v_mfma_f32_16x16x32_bf16 v[36:39], v[168:171], v[192:195], v[36:39]
	v_mfma_f32_16x16x32_bf16 v[32:35], v[176:179], v[192:195], v[32:35]
	v_mfma_f32_16x16x32_bf16 v[20:23], v[168:171], v[200:203], v[20:23]
	v_mfma_f32_16x16x32_bf16 v[16:19], v[176:179], v[200:203], v[16:19]
	v_mfma_f32_16x16x32_bf16 v[4:7], v[168:171], v[208:211], v[4:7]
	v_mfma_f32_16x16x32_bf16 v[0:3], v[176:179], v[208:211], v[0:3]
	v_mfma_f32_16x16x32_bf16 v[52:55], v[172:175], v[188:191], v[52:55]
	v_mfma_f32_16x16x32_bf16 v[48:51], v[180:183], v[188:191], v[48:51]
	v_mfma_f32_16x16x32_bf16 v[36:39], v[172:175], v[196:199], v[36:39]
	v_mfma_f32_16x16x32_bf16 v[32:35], v[180:183], v[196:199], v[32:35]
	v_mfma_f32_16x16x32_bf16 v[20:23], v[172:175], v[204:207], v[20:23]
	v_mfma_f32_16x16x32_bf16 v[16:19], v[180:183], v[204:207], v[16:19]
	v_mfma_f32_16x16x32_bf16 v[4:7], v[172:175], v[212:215], v[4:7]
	v_mfma_f32_16x16x32_bf16 v[0:3], v[180:183], v[212:215], v[0:3]
	s_barrier
; #define PG8_STAGE(bufoff, gbase, voff) do { _Pragma("unroll") for (int _i = 0; _i < 2; ++_i) \
;         __builtin_amdgcn_global_load_lds((const unsigned*)((const char*)(gbase) + (voff)[_i]), (PG8_LAS unsigned*)(lds + (bufoff) + ldsw + _i * 8192), 16, 0, 0); } while (0)
; #define PG8_LDA(dst, b, h) do { _Pragma("unroll") for (int m = 0; m < 4; ++m) _Pragma("unroll") for (int k = 0; k < 2; ++k) dst[m][k] = *(const PG8_LAS bf16x8*)(lds + PG8_SA(b, h) + aoff + m * 2048 + k * 1024); } while (0)
; #define PG8_LDB(dst, b, h) do { _Pragma("unroll") for (int n = 0; n < 2; ++n) _Pragma("unroll") for (int k = 0; k < 2; ++k) dst[n][k] = *(const PG8_LAS bf16x8*)(lds + PG8_SB(b, h) + boff + n * 2048 + k * 1024); } while (0)
; #define PG8_MMA(ai, bj, At, Bt) do { __builtin_amdgcn_s_setprio(1); _Pragma("unroll") for (int m = 0; m < 4; ++m) _Pragma("unroll") for (int n = 0; n < 2; ++n) _Pragma("unroll") for (int k = 0; k < 2; ++k) \
;         acc[ai][bj][m][n] = __builtin_amdgcn_mfma_f32_16x16x32_bf16(Bt[n][k], At[m][k], acc[ai][bj][m][n], 0, 0, 0); __builtin_amdgcn_s_setprio(0); } while (0)
; #define PG8_WAIT_V(n) asm volatile("s_waitcnt vmcnt(" #n ")" ::: "memory")
; #define PG8_WAIT_L(n) asm volatile("s_waitcnt lgkmcnt(" #n ")" ::: "memory")
; #define PG8_BAR __builtin_amdgcn_s_barrier()
; #define PG8_SCHED __builtin_amdgcn_sched_barrier(0)
; template <class Epi, class Sched, bool ALIGN_EPI = false, bool SP2 = false>
; __device__ __forceinline__ void gemm_phase(PG8_LAS unsigned char* lds, const Gemm g, const Sched& S, const Epi& E) {
;     ...
;             PG8_LDB(B0, 1, 0); PG8_LDB(B1, 1, 1); PG8_SCHED; PG8_LDA(At, 1, 0); PG8_STAGE(PG8_SA(0, 1), a2 + hstep, voffA);
;             PG8_WAIT_V(8); PG8_WAIT_L(0); PG8_BAR; PG8_MMA(0, 0, At, B0); PG8_MMA(0, 1, At, B1); PG8_BAR; PG8_SCHED;
;             PG8_LDA(At, 1, 1); PG8_STAGE(PG8_SB(1, 0), b3, voffB); PG8_STAGE(PG8_SB(1, 1), b3 + hstep, voffB); PG8_STAGE(PG8_SA(1, 0), a3, voffA);
;             PG8_WAIT_V(8); PG8_WAIT_L(0); PG8_BAR; PG8_MMA(1, 0, At, B0); PG8_MMA(1, 1, At, B1); PG8_BAR; PG8_SCHED;
	s_add_i32 s58, 0, 0x18000
	s_add_i32 s59, 0, 0x1c000
	v_add_u32_e32 v164, s58, v151
	v_add_u32_e32 v180, s59, v151
	ds_read_b128 v[144:147], v164
	ds_read_b128 v[156:159], v164 offset:1024
	ds_read_b128 v[160:163], v164 offset:2048
	ds_read_b128 v[164:167], v164 offset:3072
	ds_read_b128 v[168:171], v180
	ds_read_b128 v[172:175], v180 offset:1024
	ds_read_b128 v[176:179], v180 offset:2048
	ds_read_b128 v[180:183], v180 offset:3072
	s_add_u32 s28, s28, 0x160000
	s_addc_u32 s29, s29, 0
	s_mov_b32 m0, s39
	ds_read_b128 v[184:187], v155 offset:32768
	ds_read_b128 v[188:191], v155 offset:33792
	ds_read_b128 v[192:195], v155 offset:34816
	ds_read_b128 v[196:199], v155 offset:35840
	ds_read_b128 v[200:203], v155 offset:36864
	ds_read_b128 v[204:207], v155 offset:37888
	ds_read_b128 v[208:211], v155 offset:38912
	ds_read_b128 v[212:215], v155 offset:39936
	global_load_lds_dwordx4 v128, s[28:29]
	s_mov_b32 m0, s40
	s_nop 0
	global_load_lds_dwordx4 v132, s[28:29]
	s_waitcnt vmcnt(8)
	s_waitcnt lgkmcnt(0)
	s_barrier
	s_waitcnt lgkmcnt(0)
	v_mfma_f32_16x16x32_bf16 v[124:127], v[144:147], v[184:187], v[124:127]
	v_mfma_f32_16x16x32_bf16 v[120:123], v[160:163], v[184:187], v[120:123]
	v_mfma_f32_16x16x32_bf16 v[108:111], v[144:147], v[192:195], v[108:111]
	v_mfma_f32_16x16x32_bf16 v[104:107], v[160:163], v[192:195], v[104:107]
	v_mfma_f32_16x16x32_bf16 v[92:95], v[144:147], v[200:203], v[92:95]
	v_mfma_f32_16x16x32_bf16 v[88:91], v[160:163], v[200:203], v[88:91]
	v_mfma_f32_16x16x32_bf16 v[76:79], v[144:147], v[208:211], v[76:79]
	v_mfma_f32_16x16x32_bf16 v[72:75], v[160:163], v[208:211], v[72:75]
	v_mfma_f32_16x16x32_bf16 v[124:127], v[156:159], v[188:191], v[124:127]
	v_mfma_f32_16x16x32_bf16 v[120:123], v[164:167], v[188:191], v[120:123]
	v_mfma_f32_16x16x32_bf16 v[108:111], v[156:159], v[196:199], v[108:111]
	v_mfma_f32_16x16x32_bf16 v[104:107], v[164:167], v[196:199], v[104:107]
	v_mfma_f32_16x16x32_bf16 v[92:95], v[156:159], v[204:207], v[92:95]
	v_mfma_f32_16x16x32_bf16 v[88:91], v[164:167], v[204:207], v[88:91]
	v_mfma_f32_16x16x32_bf16 v[76:79], v[156:159], v[212:215], v[76:79]
	v_mfma_f32_16x16x32_bf16 v[72:75], v[164:167], v[212:215], v[72:75]
	v_mfma_f32_16x16x32_bf16 v[116:119], v[168:171], v[184:187], v[116:119]
	v_mfma_f32_16x16x32_bf16 v[112:115], v[176:179], v[184:187], v[112:115]
	v_mfma_f32_16x16x32_bf16 v[100:103], v[168:171], v[192:195], v[100:103]
	v_mfma_f32_16x16x32_bf16 v[96:99], v[176:179], v[192:195], v[96:99]
	v_mfma_f32_16x16x32_bf16 v[84:87], v[168:171], v[200:203], v[84:87]
	v_mfma_f32_16x16x32_bf16 v[80:83], v[176:179], v[200:203], v[80:83]
	v_mfma_f32_16x16x32_bf16 v[68:71], v[168:171], v[208:211], v[68:71]
	v_mfma_f32_16x16x32_bf16 v[64:67], v[176:179], v[208:211], v[64:67]
	v_mfma_f32_16x16x32_bf16 v[116:119], v[172:175], v[188:191], v[116:119]
	v_mfma_f32_16x16x32_bf16 v[112:115], v[180:183], v[188:191], v[112:115]
	v_mfma_f32_16x16x32_bf16 v[100:103], v[172:175], v[196:199], v[100:103]
	v_mfma_f32_16x16x32_bf16 v[96:99], v[180:183], v[196:199], v[96:99]
	v_mfma_f32_16x16x32_bf16 v[84:87], v[172:175], v[204:207], v[84:87]
	v_mfma_f32_16x16x32_bf16 v[80:83], v[180:183], v[204:207], v[80:83]
	v_mfma_f32_16x16x32_bf16 v[68:71], v[172:175], v[212:215], v[68:71]
	v_mfma_f32_16x16x32_bf16 v[64:67], v[180:183], v[212:215], v[64:67]
	s_barrier
	s_mov_b64 s[62:63], s[28:29]
	s_add_i32 s28, s58, s36
	s_mov_b32 m0, s28
	ds_read_b128 v[184:187], v155 offset:49152
	ds_read_b128 v[188:191], v155 offset:50176
	ds_read_b128 v[192:195], v155 offset:51200
	ds_read_b128 v[196:199], v155 offset:52224
	ds_read_b128 v[200:203], v155 offset:53248
	ds_read_b128 v[204:207], v155 offset:54272
	ds_read_b128 v[208:211], v155 offset:55296
	ds_read_b128 v[212:215], v155 offset:56320
	s_add_u32 s64, s24, 0x80
	s_addc_u32 s65, s25, 0
	global_load_lds_dwordx4 v130, s[64:65]
	s_add_i32 m0, s28, 0x2000
	s_add_u32 s24, s24, 0x160080
	s_addc_u32 s25, s25, 0
	s_add_i32 s28, s59, s36
	global_load_lds_dwordx4 v134, s[64:65]
	s_mov_b32 m0, s28
	s_nop 0
	global_load_lds_dwordx4 v130, s[24:25]
	s_add_i32 m0, s28, 0x2000
	s_nop 0
	global_load_lds_dwordx4 v134, s[24:25]
	s_mov_b32 m0, s42
	s_nop 0
	s_add_u32 s66, s62, 0xffea0080
	s_addc_u32 s67, s63, -1
	global_load_lds_dwordx4 v128, s[66:67]
	s_mov_b32 m0, s43
	s_nop 0
	global_load_lds_dwordx4 v132, s[66:67]
	s_waitcnt vmcnt(8)
	s_waitcnt lgkmcnt(0)
	s_barrier
	s_waitcnt lgkmcnt(0)
	v_mfma_f32_16x16x32_bf16 v[60:63], v[144:147], v[184:187], v[60:63]
	v_mfma_f32_16x16x32_bf16 v[56:59], v[160:163], v[184:187], v[56:59]
	v_mfma_f32_16x16x32_bf16 v[44:47], v[144:147], v[192:195], v[44:47]
	v_mfma_f32_16x16x32_bf16 v[40:43], v[160:163], v[192:195], v[40:43]
	v_mfma_f32_16x16x32_bf16 v[28:31], v[144:147], v[200:203], v[28:31]
	v_mfma_f32_16x16x32_bf16 v[24:27], v[160:163], v[200:203], v[24:27]
	v_mfma_f32_16x16x32_bf16 v[12:15], v[144:147], v[208:211], v[12:15]
	v_mfma_f32_16x16x32_bf16 v[8:11], v[160:163], v[208:211], v[8:11]
	v_mfma_f32_16x16x32_bf16 v[60:63], v[156:159], v[188:191], v[60:63]
	v_mfma_f32_16x16x32_bf16 v[56:59], v[164:167], v[188:191], v[56:59]
	v_mfma_f32_16x16x32_bf16 v[44:47], v[156:159], v[196:199], v[44:47]
	v_mfma_f32_16x16x32_bf16 v[40:43], v[164:167], v[196:199], v[40:43]
	v_mfma_f32_16x16x32_bf16 v[28:31], v[156:159], v[204:207], v[28:31]
	v_mfma_f32_16x16x32_bf16 v[24:27], v[164:167], v[204:207], v[24:27]
	v_mfma_f32_16x16x32_bf16 v[12:15], v[156:159], v[212:215], v[12:15]
	v_mfma_f32_16x16x32_bf16 v[8:11], v[164:167], v[212:215], v[8:11]
	v_mfma_f32_16x16x32_bf16 v[52:55], v[168:171], v[184:187], v[52:55]
	v_mfma_f32_16x16x32_bf16 v[48:51], v[176:179], v[184:187], v[48:51]
	v_mfma_f32_16x16x32_bf16 v[36:39], v[168:171], v[192:195], v[36:39]
	v_mfma_f32_16x16x32_bf16 v[32:35], v[176:179], v[192:195], v[32:35]
	v_mfma_f32_16x16x32_bf16 v[20:23], v[168:171], v[200:203], v[20:23]
	v_mfma_f32_16x16x32_bf16 v[16:19], v[176:179], v[200:203], v[16:19]
	v_mfma_f32_16x16x32_bf16 v[4:7], v[168:171], v[208:211], v[4:7]
	v_mfma_f32_16x16x32_bf16 v[0:3], v[176:179], v[208:211], v[0:3]
	v_mfma_f32_16x16x32_bf16 v[52:55], v[172:175], v[188:191], v[52:55]
	v_mfma_f32_16x16x32_bf16 v[48:51], v[180:183], v[188:191], v[48:51]
	v_mfma_f32_16x16x32_bf16 v[36:39], v[172:175], v[196:199], v[36:39]
	v_mfma_f32_16x16x32_bf16 v[32:35], v[180:183], v[196:199], v[32:35]
	v_mfma_f32_16x16x32_bf16 v[20:23], v[172:175], v[204:207], v[20:23]
	v_mfma_f32_16x16x32_bf16 v[16:19], v[180:183], v[204:207], v[16:19]
	v_mfma_f32_16x16x32_bf16 v[4:7], v[172:175], v[212:215], v[4:7]
	v_mfma_f32_16x16x32_bf16 v[0:3], v[180:183], v[212:215], v[0:3]
	s_barrier
	s_add_i32 s57, s57, 2
	s_add_u32 s22, s22, 0x100
	s_addc_u32 s23, s23, 0
	s_add_u32 s55, s55, 0x100
	s_addc_u32 s56, s56, 0
	s_cmpk_gt_u32 s57, 0x55
	s_cbranch_scc0 .LBB0_742
	s_and_b64 vcc, exec, s[12:13]
	s_cbranch_vccz .LBB0_745
	s_barrier
